# nt hint on the write-once outputs of the gemm_out and MoE down-projection epilogues
# speedup vs baseline: 1.0072x; 1.0072x over previous
; DI void gemm_out_phase(const Params& P, int l, char* smem) {
;     ...
;     {
;       float* stg = (float*)(smem + 98304 + wave2 * 12288);
; #pragma unroll
;       for (int q = 0; q < 4; q++) {
; #pragma unroll
;         for (int ml = 0; ml < 2; ml++)
; #pragma unroll
;           for (int nn = 0; nn < 4; nn++)
; #pragma unroll
;             for (int j = 0; j < 4; j++) stg[(ml * 16 + fq2 * 4 + j) * 68 + nn * 16 + fr2] = acc[q * 2 + ml][nn][j];
;         __builtin_amdgcn_wave_barrier();
; #pragma unroll
;         for (int i = 0; i < 8; i++) {
;           const int row = i * 4 + fq2;
;           const float4 a = *(const float4*)(stg + row * 68 + fr2 * 4);
;           float4 r = rres[q][i];
;           r.x += g4.x * a.x; r.y += g4.y * a.y; r.z += g4.z * a.z; r.w += g4.w * a.w;
;           *(float4*)(dst + (size_t)(q * 32 + row) * D) = r;
;         }
.LBB0_512:
	v_lshl_add_u64 v[144:145], v[144:145], 2, v[140:141]
	s_nop 1
	v_readfirstlane_b32 s48, v144
	v_readfirstlane_b32 s49, v145
	s_add_u32 s50, s90, 0xf05c700
	s_addc_u32 s51, s91, 0
	s_sub_u32 s52, s48, s50
	s_subb_u32 s53, s49, s51
	s_cmp_eq_u32 s53, 0
	s_cselect_b32 s52, s52, -1
	v_readlane_b32 s55, v253, 49
	s_cmp_lt_u32 s52, 0x800000
	s_cselect_b32 s50, s50, s55
	s_cselect_b32 s54, 0x400000, 0
	s_cselect_b32 s60, 13, 18
	s_add_u32 s52, s90, 0x200bc700
	s_addc_u32 s53, s91, 0
	s_add_u32 s52, s52, s54
	s_addc_u32 s53, s53, 0
	s_mov_b32 s58, 0x10001
	s_mov_b32 s59, 0x10001
	v_lshrrev_b32_e32 v140, 6, v150
	s_movk_i32 s2, 0x3000
	v_mul_lo_u32 v140, v140, s2
	v_lshl_or_b32 v140, v152, 2, v140
	v_add_u32_e32 v140, 0x18000, v140
	v_mad_u32_u24 v156, v152, 12, v140
	s_movk_i32 s3, 0x110
	s_movk_i32 s2, 0x440
	v_mad_u32_u24 v143, v151, s3, v156
	v_mad_u32_u24 v150, v151, s2, v140
	s_waitcnt vmcnt(0)
	ds_write_b32 v150, a124
	ds_write_b32 v150, a125 offset:272
	ds_write_b32 v150, a126 offset:544
	ds_write_b32 v150, a127 offset:816
	ds_write_b32 v150, a120 offset:64
	ds_write_b32 v150, a121 offset:336
	ds_write_b32 v150, a122 offset:608
	ds_write_b32 v150, a123 offset:880
	ds_write_b32 v150, a116 offset:128
	ds_write_b32 v150, a117 offset:400
	ds_write_b32 v150, a118 offset:672
	ds_write_b32 v150, a119 offset:944
	ds_write_b32 v150, a112 offset:192
	ds_write_b32 v150, a113 offset:464
	ds_write_b32 v150, a114 offset:736
	ds_write_b32 v150, a115 offset:1008
	ds_write_b32 v150, a108 offset:4352
	ds_write_b32 v150, a109 offset:4624
	ds_write_b32 v150, a110 offset:4896
	ds_write_b32 v150, a111 offset:5168
	ds_write_b32 v150, a104 offset:4416
	ds_write_b32 v150, a105 offset:4688
	ds_write_b32 v150, a106 offset:4960
	ds_write_b32 v150, a107 offset:5232
	ds_write_b32 v150, a100 offset:4480
	ds_write_b32 v150, a101 offset:4752
	ds_write_b32 v150, a102 offset:5024
	ds_write_b32 v150, a103 offset:5296
	ds_write_b32 v150, a96 offset:4544
	ds_write_b32 v150, a97 offset:4816
	ds_write_b32 v150, a98 offset:5088
	ds_write_b32 v150, a99 offset:5360
	ds_read_b128 v[152:155], v143
	v_lshlrev_b32_e32 v148, 2, v146
	v_lshl_add_u64 v[140:141], v[144:145], 0, v[148:149]
	s_mov_b32 s2, 0x60000
	s_waitcnt lgkmcnt(0)
	v_pk_fma_f32 v[128:129], v[0:1], v[152:153], v[128:129]
	v_pk_fma_f32 v[130:131], v[2:3], v[154:155], v[130:131]
	v_mul_f32_e32 v186, v128, v128
	v_fmac_f32_e32 v186, v129, v129
	v_fmac_f32_e32 v186, v130, v130
	v_fmac_f32_e32 v186, v131, v131
	v_subrev_u32_e32 v187, s50, v140
	v_bfe_u32 v188, v187, 8, 4
	s_nop 1
	v_add_f32_dpp v186, v186, v186 row_ror:8 row_mask:0xf bank_mask:0xf
	s_nop 1
	v_add_f32_dpp v186, v186, v186 row_ror:4 row_mask:0xf bank_mask:0xf
	s_nop 1
	v_add_f32_dpp v186, v186, v186 row_ror:2 row_mask:0xf bank_mask:0xf
	s_nop 1
	v_add_f32_dpp v186, v186, v186 row_ror:1 row_mask:0xf bank_mask:0xf
	v_lshrrev_b32_e32 v187, 12, v187
	v_lshlrev_b32_e32 v187, 2, v187
	v_lshl_add_u32 v187, v188, s60, v187
	s_mov_b64 s[56:57], exec
	s_mov_b64 exec, s[58:59]
	global_store_dword v187, v186, s[52:53]
	s_mov_b64 exec, s[56:57]
	global_store_dwordx4 v[140:141], v[128:131], off nt
	s_nop 1
	v_or_b32_e32 v128, 4, v151
	v_mad_u32_u24 v130, v128, s3, v156
	ds_read_b128 v[152:155], v130
	v_lshlrev_b32_e32 v148, 12, v128
	v_lshl_add_u64 v[128:129], v[144:145], 0, v[148:149]
	v_or_b32_e32 v148, 0x8000, v142
	s_waitcnt lgkmcnt(0)
	v_pk_fma_f32 v[124:125], v[0:1], v[152:153], v[124:125]
	v_pk_fma_f32 v[126:127], v[2:3], v[154:155], v[126:127]
	ds_read_b128 v[152:155], v130 offset:1088
	v_mul_f32_e32 v186, v124, v124
	v_fmac_f32_e32 v186, v125, v125
	v_fmac_f32_e32 v186, v126, v126
	v_fmac_f32_e32 v186, v127, v127
	v_subrev_u32_e32 v187, s50, v128
	v_bfe_u32 v188, v187, 8, 4
	s_nop 1
	v_add_f32_dpp v186, v186, v186 row_ror:8 row_mask:0xf bank_mask:0xf
	s_nop 1
	v_add_f32_dpp v186, v186, v186 row_ror:4 row_mask:0xf bank_mask:0xf
	s_nop 1
	v_add_f32_dpp v186, v186, v186 row_ror:2 row_mask:0xf bank_mask:0xf
	s_nop 1
	v_add_f32_dpp v186, v186, v186 row_ror:1 row_mask:0xf bank_mask:0xf
	v_lshrrev_b32_e32 v187, 12, v187
	v_lshlrev_b32_e32 v187, 2, v187
	v_lshl_add_u32 v187, v188, s60, v187
	s_mov_b64 s[56:57], exec
	s_mov_b64 exec, s[58:59]
	global_store_dword v187, v186, s[52:53]
	s_mov_b64 exec, s[56:57]
	global_store_dwordx4 v[128:129], v[124:127], off nt
	s_waitcnt lgkmcnt(0)
	v_pk_fma_f32 v[120:121], v[0:1], v[152:153], v[120:121]
	v_pk_fma_f32 v[122:123], v[2:3], v[154:155], v[122:123]
	ds_read_b128 v[152:155], v130 offset:2176
	v_lshl_add_u64 v[124:125], v[144:145], 0, v[148:149]
	v_or_b32_e32 v148, 0xc000, v142
	v_mul_f32_e32 v186, v120, v120
	v_fmac_f32_e32 v186, v121, v121
	v_fmac_f32_e32 v186, v122, v122
	v_fmac_f32_e32 v186, v123, v123
	v_subrev_u32_e32 v187, s50, v124
	v_bfe_u32 v188, v187, 8, 4
	s_nop 1
	v_add_f32_dpp v186, v186, v186 row_ror:8 row_mask:0xf bank_mask:0xf
	s_nop 1
	v_add_f32_dpp v186, v186, v186 row_ror:4 row_mask:0xf bank_mask:0xf
	s_nop 1
	v_add_f32_dpp v186, v186, v186 row_ror:2 row_mask:0xf bank_mask:0xf
	s_nop 1
	v_add_f32_dpp v186, v186, v186 row_ror:1 row_mask:0xf bank_mask:0xf
	v_lshrrev_b32_e32 v187, 12, v187
	v_lshlrev_b32_e32 v187, 2, v187
	v_lshl_add_u32 v187, v188, s60, v187
	s_mov_b64 s[56:57], exec
	s_mov_b64 exec, s[58:59]
	global_store_dword v187, v186, s[52:53]
	s_mov_b64 exec, s[56:57]
	global_store_dwordx4 v[124:125], v[120:123], off nt
	s_waitcnt lgkmcnt(0)
; DI void gemm_out_phase(const Params& P, int l, char* smem) {
;     ...
;     {
;       float* stg = (float*)(smem + 98304 + wave2 * 12288);
; #pragma unroll
;       for (int q = 0; q < 4; q++) {
; #pragma unroll
;         for (int ml = 0; ml < 2; ml++)
; #pragma unroll
;           for (int nn = 0; nn < 4; nn++)
; #pragma unroll
;             for (int j = 0; j < 4; j++) stg[(ml * 16 + fq2 * 4 + j) * 68 + nn * 16 + fr2] = acc[q * 2 + ml][nn][j];
;         __builtin_amdgcn_wave_barrier();
; #pragma unroll
;         for (int i = 0; i < 8; i++) {
;           const int row = i * 4 + fq2;
;           const float4 a = *(const float4*)(stg + row * 68 + fr2 * 4);
;           float4 r = rres[q][i];
;           r.x += g4.x * a.x; r.y += g4.y * a.y; r.z += g4.z * a.z; r.w += g4.w * a.w;
;           *(float4*)(dst + (size_t)(q * 32 + row) * D) = r;
;         }
	v_pk_fma_f32 v[116:117], v[0:1], v[152:153], v[116:117]
	v_pk_fma_f32 v[118:119], v[2:3], v[154:155], v[118:119]
	ds_read_b128 v[152:155], v130 offset:3264
	v_lshl_add_u64 v[120:121], v[144:145], 0, v[148:149]
	v_or_b32_e32 v148, 0x10000, v142
	v_mul_f32_e32 v186, v116, v116
	v_fmac_f32_e32 v186, v117, v117
	v_fmac_f32_e32 v186, v118, v118
	v_fmac_f32_e32 v186, v119, v119
	v_subrev_u32_e32 v187, s50, v120
	v_bfe_u32 v188, v187, 8, 4
	s_nop 1
	v_add_f32_dpp v186, v186, v186 row_ror:8 row_mask:0xf bank_mask:0xf
	s_nop 1
	v_add_f32_dpp v186, v186, v186 row_ror:4 row_mask:0xf bank_mask:0xf
	s_nop 1
	v_add_f32_dpp v186, v186, v186 row_ror:2 row_mask:0xf bank_mask:0xf
	s_nop 1
	v_add_f32_dpp v186, v186, v186 row_ror:1 row_mask:0xf bank_mask:0xf
	v_lshrrev_b32_e32 v187, 12, v187
	v_lshlrev_b32_e32 v187, 2, v187
	v_lshl_add_u32 v187, v188, s60, v187
	s_mov_b64 s[56:57], exec
	s_mov_b64 exec, s[58:59]
	global_store_dword v187, v186, s[52:53]
	s_mov_b64 exec, s[56:57]
	global_store_dwordx4 v[120:121], v[116:119], off nt
	s_waitcnt lgkmcnt(0)
	v_pk_fma_f32 v[112:113], v[0:1], v[152:153], v[112:113]
	v_pk_fma_f32 v[114:115], v[2:3], v[154:155], v[114:115]
	ds_read_b128 v[152:155], v130 offset:4352
	v_lshl_add_u64 v[116:117], v[144:145], 0, v[148:149]
	v_or_b32_e32 v148, 0x14000, v142
	v_mul_f32_e32 v186, v112, v112
	v_fmac_f32_e32 v186, v113, v113
	v_fmac_f32_e32 v186, v114, v114
	v_fmac_f32_e32 v186, v115, v115
	v_subrev_u32_e32 v187, s50, v116
	v_bfe_u32 v188, v187, 8, 4
	s_nop 1
	v_add_f32_dpp v186, v186, v186 row_ror:8 row_mask:0xf bank_mask:0xf
	s_nop 1
	v_add_f32_dpp v186, v186, v186 row_ror:4 row_mask:0xf bank_mask:0xf
	s_nop 1
	v_add_f32_dpp v186, v186, v186 row_ror:2 row_mask:0xf bank_mask:0xf
	s_nop 1
	v_add_f32_dpp v186, v186, v186 row_ror:1 row_mask:0xf bank_mask:0xf
	v_lshrrev_b32_e32 v187, 12, v187
	v_lshlrev_b32_e32 v187, 2, v187
	v_lshl_add_u32 v187, v188, s60, v187
	s_mov_b64 s[56:57], exec
	s_mov_b64 exec, s[58:59]
	global_store_dword v187, v186, s[52:53]
	s_mov_b64 exec, s[56:57]
	global_store_dwordx4 v[116:117], v[112:115], off nt
	s_waitcnt lgkmcnt(0)
	v_pk_fma_f32 v[108:109], v[0:1], v[152:153], v[108:109]
	v_pk_fma_f32 v[110:111], v[2:3], v[154:155], v[110:111]
	ds_read_b128 v[152:155], v130 offset:5440
	v_lshl_add_u64 v[112:113], v[144:145], 0, v[148:149]
	v_or_b32_e32 v148, 0x18000, v142
	v_mul_f32_e32 v186, v108, v108
	v_fmac_f32_e32 v186, v109, v109
	v_fmac_f32_e32 v186, v110, v110
	v_fmac_f32_e32 v186, v111, v111
	v_subrev_u32_e32 v187, s50, v112
	v_bfe_u32 v188, v187, 8, 4
	s_nop 1
	v_add_f32_dpp v186, v186, v186 row_ror:8 row_mask:0xf bank_mask:0xf
	s_nop 1
	v_add_f32_dpp v186, v186, v186 row_ror:4 row_mask:0xf bank_mask:0xf
	s_nop 1
	v_add_f32_dpp v186, v186, v186 row_ror:2 row_mask:0xf bank_mask:0xf
	s_nop 1
	v_add_f32_dpp v186, v186, v186 row_ror:1 row_mask:0xf bank_mask:0xf
	v_lshrrev_b32_e32 v187, 12, v187
	v_lshlrev_b32_e32 v187, 2, v187
	v_lshl_add_u32 v187, v188, s60, v187
	s_mov_b64 s[56:57], exec
	s_mov_b64 exec, s[58:59]
	global_store_dword v187, v186, s[52:53]
	s_mov_b64 exec, s[56:57]
	global_store_dwordx4 v[112:113], v[108:111], off nt
	s_waitcnt lgkmcnt(0)
	v_pk_fma_f32 v[104:105], v[0:1], v[152:153], v[104:105]
	v_pk_fma_f32 v[106:107], v[2:3], v[154:155], v[106:107]
	ds_read_b128 v[152:155], v130 offset:6528
	v_lshl_add_u64 v[108:109], v[144:145], 0, v[148:149]
	v_or_b32_e32 v148, 0x1c000, v142
	v_mul_f32_e32 v186, v104, v104
	v_fmac_f32_e32 v186, v105, v105
	v_fmac_f32_e32 v186, v106, v106
	v_fmac_f32_e32 v186, v107, v107
	v_subrev_u32_e32 v187, s50, v108
	v_bfe_u32 v188, v187, 8, 4
	s_nop 1
	v_add_f32_dpp v186, v186, v186 row_ror:8 row_mask:0xf bank_mask:0xf
	s_nop 1
	v_add_f32_dpp v186, v186, v186 row_ror:4 row_mask:0xf bank_mask:0xf
	s_nop 1
	v_add_f32_dpp v186, v186, v186 row_ror:2 row_mask:0xf bank_mask:0xf
	s_nop 1
	v_add_f32_dpp v186, v186, v186 row_ror:1 row_mask:0xf bank_mask:0xf
	v_lshrrev_b32_e32 v187, 12, v187
	v_lshlrev_b32_e32 v187, 2, v187
	v_lshl_add_u32 v187, v188, s60, v187
	s_mov_b64 s[56:57], exec
	s_mov_b64 exec, s[58:59]
	global_store_dword v187, v186, s[52:53]
	s_mov_b64 exec, s[56:57]
	global_store_dwordx4 v[108:109], v[104:107], off nt
	s_waitcnt lgkmcnt(0)
	v_pk_fma_f32 v[100:101], v[0:1], v[152:153], v[100:101]
	v_lshl_add_u64 v[104:105], v[144:145], 0, v[148:149]
	v_pk_fma_f32 v[102:103], v[2:3], v[154:155], v[102:103]
	v_mul_f32_e32 v186, v100, v100
	v_fmac_f32_e32 v186, v101, v101
	v_fmac_f32_e32 v186, v102, v102
	v_fmac_f32_e32 v186, v103, v103
	v_subrev_u32_e32 v187, s50, v104
	v_bfe_u32 v188, v187, 8, 4
	s_nop 1
	v_add_f32_dpp v186, v186, v186 row_ror:8 row_mask:0xf bank_mask:0xf
	s_nop 1
	v_add_f32_dpp v186, v186, v186 row_ror:4 row_mask:0xf bank_mask:0xf
	s_nop 1
	v_add_f32_dpp v186, v186, v186 row_ror:2 row_mask:0xf bank_mask:0xf
	s_nop 1
	v_add_f32_dpp v186, v186, v186 row_ror:1 row_mask:0xf bank_mask:0xf
	v_lshrrev_b32_e32 v187, 12, v187
	v_lshlrev_b32_e32 v187, 2, v187
	v_lshl_add_u32 v187, v188, s60, v187
	s_mov_b64 s[56:57], exec
	s_mov_b64 exec, s[58:59]
	global_store_dword v187, v186, s[52:53]
	s_mov_b64 exec, s[56:57]
	global_store_dwordx4 v[104:105], v[100:103], off nt
	ds_write_b32 v150, a92
	ds_write_b32 v150, a93 offset:272
	ds_write_b32 v150, a94 offset:544
	ds_write_b32 v150, a95 offset:816
	ds_write_b32 v150, a88 offset:64
	ds_write_b32 v150, a89 offset:336
	ds_write_b32 v150, a90 offset:608
	ds_write_b32 v150, a91 offset:880
	ds_write_b32 v150, a84 offset:128
	ds_write_b32 v150, a85 offset:400
	ds_write_b32 v150, a86 offset:672
	ds_write_b32 v150, a87 offset:944
	ds_write_b32 v150, a80 offset:192
	ds_write_b32 v150, a81 offset:464
	ds_write_b32 v150, a82 offset:736
	ds_write_b32 v150, a83 offset:1008
	ds_write_b32 v150, a76 offset:4352
	ds_write_b32 v150, a77 offset:4624
	ds_write_b32 v150, a78 offset:4896
	ds_write_b32 v150, a79 offset:5168
	ds_write_b32 v150, a72 offset:4416
	ds_write_b32 v150, a73 offset:4688
	ds_write_b32 v150, a74 offset:4960
	ds_write_b32 v150, a75 offset:5232
	ds_write_b32 v150, a68 offset:4480
	ds_write_b32 v150, a69 offset:4752
	ds_write_b32 v150, a70 offset:5024
	ds_write_b32 v150, a71 offset:5296
	ds_write_b32 v150, a64 offset:4544
	ds_write_b32 v150, a65 offset:4816
	ds_write_b32 v150, a66 offset:5088
	ds_write_b32 v150, a67 offset:5360
	ds_read_b128 v[100:103], v143
	s_waitcnt lgkmcnt(0)
; DI void gemm_out_phase(const Params& P, int l, char* smem) {
;     ...
;     {
;       float* stg = (float*)(smem + 98304 + wave2 * 12288);
; #pragma unroll
;       for (int q = 0; q < 4; q++) {
; #pragma unroll
;         for (int ml = 0; ml < 2; ml++)
; #pragma unroll
;           for (int nn = 0; nn < 4; nn++)
; #pragma unroll
;             for (int j = 0; j < 4; j++) stg[(ml * 16 + fq2 * 4 + j) * 68 + nn * 16 + fr2] = acc[q * 2 + ml][nn][j];
;         __builtin_amdgcn_wave_barrier();
; #pragma unroll
;         for (int i = 0; i < 8; i++) {
;           const int row = i * 4 + fq2;
;           const float4 a = *(const float4*)(stg + row * 68 + fr2 * 4);
;           float4 r = rres[q][i];
;           r.x += g4.x * a.x; r.y += g4.y * a.y; r.z += g4.z * a.z; r.w += g4.w * a.w;
;           *(float4*)(dst + (size_t)(q * 32 + row) * D) = r;
;         }
	v_pk_fma_f32 v[96:97], v[0:1], v[100:101], v[96:97]
	v_add_co_u32_e32 v100, vcc, s31, v140
	v_pk_fma_f32 v[98:99], v[2:3], v[102:103], v[98:99]
	s_nop 0
	v_addc_co_u32_e32 v101, vcc, 0, v141, vcc
	v_mul_f32_e32 v186, v96, v96
	v_fmac_f32_e32 v186, v97, v97
	v_fmac_f32_e32 v186, v98, v98
	v_fmac_f32_e32 v186, v99, v99
	v_subrev_u32_e32 v187, s50, v100
	v_bfe_u32 v188, v187, 8, 4
	s_nop 1
	v_add_f32_dpp v186, v186, v186 row_ror:8 row_mask:0xf bank_mask:0xf
	s_nop 1
	v_add_f32_dpp v186, v186, v186 row_ror:4 row_mask:0xf bank_mask:0xf
	s_nop 1
	v_add_f32_dpp v186, v186, v186 row_ror:2 row_mask:0xf bank_mask:0xf
	s_nop 1
	v_add_f32_dpp v186, v186, v186 row_ror:1 row_mask:0xf bank_mask:0xf
	v_lshrrev_b32_e32 v187, 12, v187
	v_lshlrev_b32_e32 v187, 2, v187
	v_lshl_add_u32 v187, v188, s60, v187
	s_mov_b64 s[56:57], exec
	s_mov_b64 exec, s[58:59]
	global_store_dword v187, v186, s[52:53]
	s_mov_b64 exec, s[56:57]
	global_store_dwordx4 v[100:101], v[96:99], off nt
	ds_read_b128 v[96:99], v130
	s_waitcnt lgkmcnt(0)
	v_pk_fma_f32 v[92:93], v[0:1], v[96:97], v[92:93]
	v_add_co_u32_e32 v96, vcc, s31, v128
	v_pk_fma_f32 v[94:95], v[2:3], v[98:99], v[94:95]
	s_nop 0
	v_addc_co_u32_e32 v97, vcc, 0, v129, vcc
	v_mul_f32_e32 v186, v92, v92
	v_fmac_f32_e32 v186, v93, v93
	v_fmac_f32_e32 v186, v94, v94
	v_fmac_f32_e32 v186, v95, v95
	v_subrev_u32_e32 v187, s50, v96
	v_bfe_u32 v188, v187, 8, 4
	s_nop 1
	v_add_f32_dpp v186, v186, v186 row_ror:8 row_mask:0xf bank_mask:0xf
	s_nop 1
	v_add_f32_dpp v186, v186, v186 row_ror:4 row_mask:0xf bank_mask:0xf
	s_nop 1
	v_add_f32_dpp v186, v186, v186 row_ror:2 row_mask:0xf bank_mask:0xf
	s_nop 1
	v_add_f32_dpp v186, v186, v186 row_ror:1 row_mask:0xf bank_mask:0xf
	v_lshrrev_b32_e32 v187, 12, v187
	v_lshlrev_b32_e32 v187, 2, v187
	v_lshl_add_u32 v187, v188, s60, v187
	s_mov_b64 s[56:57], exec
	s_mov_b64 exec, s[58:59]
	global_store_dword v187, v186, s[52:53]
	s_mov_b64 exec, s[56:57]
	global_store_dwordx4 v[96:97], v[92:95], off nt
	ds_read_b128 v[92:95], v130 offset:1088
	s_waitcnt lgkmcnt(0)
	v_pk_fma_f32 v[88:89], v[0:1], v[92:93], v[88:89]
	v_add_co_u32_e32 v92, vcc, s31, v124
	v_pk_fma_f32 v[90:91], v[2:3], v[94:95], v[90:91]
	s_nop 0
	v_addc_co_u32_e32 v93, vcc, 0, v125, vcc
	v_mul_f32_e32 v186, v88, v88
	v_fmac_f32_e32 v186, v89, v89
	v_fmac_f32_e32 v186, v90, v90
	v_fmac_f32_e32 v186, v91, v91
	v_subrev_u32_e32 v187, s50, v92
	v_bfe_u32 v188, v187, 8, 4
	s_nop 1
	v_add_f32_dpp v186, v186, v186 row_ror:8 row_mask:0xf bank_mask:0xf
	s_nop 1
	v_add_f32_dpp v186, v186, v186 row_ror:4 row_mask:0xf bank_mask:0xf
	s_nop 1
	v_add_f32_dpp v186, v186, v186 row_ror:2 row_mask:0xf bank_mask:0xf
	s_nop 1
	v_add_f32_dpp v186, v186, v186 row_ror:1 row_mask:0xf bank_mask:0xf
	v_lshrrev_b32_e32 v187, 12, v187
	v_lshlrev_b32_e32 v187, 2, v187
	v_lshl_add_u32 v187, v188, s60, v187
	s_mov_b64 s[56:57], exec
	s_mov_b64 exec, s[58:59]
	global_store_dword v187, v186, s[52:53]
	s_mov_b64 exec, s[56:57]
	global_store_dwordx4 v[92:93], v[88:91], off nt
	ds_read_b128 v[88:91], v130 offset:2176
	s_waitcnt lgkmcnt(0)
	v_pk_fma_f32 v[84:85], v[0:1], v[88:89], v[84:85]
	v_add_co_u32_e32 v88, vcc, s31, v120
	v_pk_fma_f32 v[86:87], v[2:3], v[90:91], v[86:87]
	s_nop 0
	v_addc_co_u32_e32 v89, vcc, 0, v121, vcc
	v_mul_f32_e32 v186, v84, v84
	v_fmac_f32_e32 v186, v85, v85
	v_fmac_f32_e32 v186, v86, v86
	v_fmac_f32_e32 v186, v87, v87
	v_subrev_u32_e32 v187, s50, v88
	v_bfe_u32 v188, v187, 8, 4
	s_nop 1
	v_add_f32_dpp v186, v186, v186 row_ror:8 row_mask:0xf bank_mask:0xf
	s_nop 1
	v_add_f32_dpp v186, v186, v186 row_ror:4 row_mask:0xf bank_mask:0xf
	s_nop 1
	v_add_f32_dpp v186, v186, v186 row_ror:2 row_mask:0xf bank_mask:0xf
	s_nop 1
	v_add_f32_dpp v186, v186, v186 row_ror:1 row_mask:0xf bank_mask:0xf
	v_lshrrev_b32_e32 v187, 12, v187
	v_lshlrev_b32_e32 v187, 2, v187
	v_lshl_add_u32 v187, v188, s60, v187
	s_mov_b64 s[56:57], exec
	s_mov_b64 exec, s[58:59]
	global_store_dword v187, v186, s[52:53]
	s_mov_b64 exec, s[56:57]
	global_store_dwordx4 v[88:89], v[84:87], off nt
	ds_read_b128 v[84:87], v130 offset:3264
	s_waitcnt lgkmcnt(0)
	v_pk_fma_f32 v[80:81], v[0:1], v[84:85], v[80:81]
	v_add_co_u32_e32 v84, vcc, s31, v116
	v_pk_fma_f32 v[82:83], v[2:3], v[86:87], v[82:83]
	s_nop 0
	v_addc_co_u32_e32 v85, vcc, 0, v117, vcc
	v_mul_f32_e32 v186, v80, v80
	v_fmac_f32_e32 v186, v81, v81
	v_fmac_f32_e32 v186, v82, v82
	v_fmac_f32_e32 v186, v83, v83
	v_subrev_u32_e32 v187, s50, v84
	v_bfe_u32 v188, v187, 8, 4
	s_nop 1
	v_add_f32_dpp v186, v186, v186 row_ror:8 row_mask:0xf bank_mask:0xf
	s_nop 1
	v_add_f32_dpp v186, v186, v186 row_ror:4 row_mask:0xf bank_mask:0xf
	s_nop 1
	v_add_f32_dpp v186, v186, v186 row_ror:2 row_mask:0xf bank_mask:0xf
	s_nop 1
	v_add_f32_dpp v186, v186, v186 row_ror:1 row_mask:0xf bank_mask:0xf
	v_lshrrev_b32_e32 v187, 12, v187
	v_lshlrev_b32_e32 v187, 2, v187
	v_lshl_add_u32 v187, v188, s60, v187
	s_mov_b64 s[56:57], exec
	s_mov_b64 exec, s[58:59]
	global_store_dword v187, v186, s[52:53]
	s_mov_b64 exec, s[56:57]
	global_store_dwordx4 v[84:85], v[80:83], off nt
	ds_read_b128 v[80:83], v130 offset:4352
	s_waitcnt lgkmcnt(0)
	v_pk_fma_f32 v[76:77], v[0:1], v[80:81], v[76:77]
	v_add_co_u32_e32 v80, vcc, s31, v112
	v_pk_fma_f32 v[78:79], v[2:3], v[82:83], v[78:79]
	s_nop 0
	v_addc_co_u32_e32 v81, vcc, 0, v113, vcc
	v_mul_f32_e32 v186, v76, v76
	v_fmac_f32_e32 v186, v77, v77
	v_fmac_f32_e32 v186, v78, v78
	v_fmac_f32_e32 v186, v79, v79
	v_subrev_u32_e32 v187, s50, v80
	v_bfe_u32 v188, v187, 8, 4
	s_nop 1
	v_add_f32_dpp v186, v186, v186 row_ror:8 row_mask:0xf bank_mask:0xf
	s_nop 1
	v_add_f32_dpp v186, v186, v186 row_ror:4 row_mask:0xf bank_mask:0xf
	s_nop 1
	v_add_f32_dpp v186, v186, v186 row_ror:2 row_mask:0xf bank_mask:0xf
	s_nop 1
	v_add_f32_dpp v186, v186, v186 row_ror:1 row_mask:0xf bank_mask:0xf
	v_lshrrev_b32_e32 v187, 12, v187
	v_lshlrev_b32_e32 v187, 2, v187
	v_lshl_add_u32 v187, v188, s60, v187
	s_mov_b64 s[56:57], exec
	s_mov_b64 exec, s[58:59]
	global_store_dword v187, v186, s[52:53]
	s_mov_b64 exec, s[56:57]
	global_store_dwordx4 v[80:81], v[76:79], off nt
	ds_read_b128 v[76:79], v130 offset:5440
	s_waitcnt lgkmcnt(0)
; DI void gemm_out_phase(const Params& P, int l, char* smem) {
;     ...
;     {
;       float* stg = (float*)(smem + 98304 + wave2 * 12288);
; #pragma unroll
;       for (int q = 0; q < 4; q++) {
; #pragma unroll
;         for (int ml = 0; ml < 2; ml++)
; #pragma unroll
;           for (int nn = 0; nn < 4; nn++)
; #pragma unroll
;             for (int j = 0; j < 4; j++) stg[(ml * 16 + fq2 * 4 + j) * 68 + nn * 16 + fr2] = acc[q * 2 + ml][nn][j];
;         __builtin_amdgcn_wave_barrier();
; #pragma unroll
;         for (int i = 0; i < 8; i++) {
;           const int row = i * 4 + fq2;
;           const float4 a = *(const float4*)(stg + row * 68 + fr2 * 4);
;           float4 r = rres[q][i];
;           r.x += g4.x * a.x; r.y += g4.y * a.y; r.z += g4.z * a.z; r.w += g4.w * a.w;
;           *(float4*)(dst + (size_t)(q * 32 + row) * D) = r;
;         }
	v_pk_fma_f32 v[72:73], v[0:1], v[76:77], v[72:73]
	v_add_co_u32_e32 v76, vcc, s31, v108
	v_pk_fma_f32 v[74:75], v[2:3], v[78:79], v[74:75]
	s_nop 0
	v_addc_co_u32_e32 v77, vcc, 0, v109, vcc
	v_mul_f32_e32 v186, v72, v72
	v_fmac_f32_e32 v186, v73, v73
	v_fmac_f32_e32 v186, v74, v74
	v_fmac_f32_e32 v186, v75, v75
	v_subrev_u32_e32 v187, s50, v76
	v_bfe_u32 v188, v187, 8, 4
	s_nop 1
	v_add_f32_dpp v186, v186, v186 row_ror:8 row_mask:0xf bank_mask:0xf
	s_nop 1
	v_add_f32_dpp v186, v186, v186 row_ror:4 row_mask:0xf bank_mask:0xf
	s_nop 1
	v_add_f32_dpp v186, v186, v186 row_ror:2 row_mask:0xf bank_mask:0xf
	s_nop 1
	v_add_f32_dpp v186, v186, v186 row_ror:1 row_mask:0xf bank_mask:0xf
	v_lshrrev_b32_e32 v187, 12, v187
	v_lshlrev_b32_e32 v187, 2, v187
	v_lshl_add_u32 v187, v188, s60, v187
	s_mov_b64 s[56:57], exec
	s_mov_b64 exec, s[58:59]
	global_store_dword v187, v186, s[52:53]
	s_mov_b64 exec, s[56:57]
	global_store_dwordx4 v[76:77], v[72:75], off nt
	ds_read_b128 v[72:75], v130 offset:6528
	s_waitcnt lgkmcnt(0)
	v_pk_fma_f32 v[68:69], v[0:1], v[72:73], v[68:69]
	v_add_co_u32_e32 v72, vcc, s31, v104
	v_pk_fma_f32 v[70:71], v[2:3], v[74:75], v[70:71]
	s_nop 0
	v_addc_co_u32_e32 v73, vcc, 0, v105, vcc
	v_mul_f32_e32 v186, v68, v68
	v_fmac_f32_e32 v186, v69, v69
	v_fmac_f32_e32 v186, v70, v70
	v_fmac_f32_e32 v186, v71, v71
	v_subrev_u32_e32 v187, s50, v72
	v_bfe_u32 v188, v187, 8, 4
	s_nop 1
	v_add_f32_dpp v186, v186, v186 row_ror:8 row_mask:0xf bank_mask:0xf
	s_nop 1
	v_add_f32_dpp v186, v186, v186 row_ror:4 row_mask:0xf bank_mask:0xf
	s_nop 1
	v_add_f32_dpp v186, v186, v186 row_ror:2 row_mask:0xf bank_mask:0xf
	s_nop 1
	v_add_f32_dpp v186, v186, v186 row_ror:1 row_mask:0xf bank_mask:0xf
	v_lshrrev_b32_e32 v187, 12, v187
	v_lshlrev_b32_e32 v187, 2, v187
	v_lshl_add_u32 v187, v188, s60, v187
	s_mov_b64 s[56:57], exec
	s_mov_b64 exec, s[58:59]
	global_store_dword v187, v186, s[52:53]
	s_mov_b64 exec, s[56:57]
	global_store_dwordx4 v[72:73], v[68:71], off nt
	ds_write_b32 v150, a60
	ds_write_b32 v150, a61 offset:272
	ds_write_b32 v150, a62 offset:544
	ds_write_b32 v150, a63 offset:816
	ds_write_b32 v150, a56 offset:64
	ds_write_b32 v150, a57 offset:336
	ds_write_b32 v150, a58 offset:608
	ds_write_b32 v150, a59 offset:880
	ds_write_b32 v150, a52 offset:128
	ds_write_b32 v150, a53 offset:400
	ds_write_b32 v150, a54 offset:672
	ds_write_b32 v150, a55 offset:944
	ds_write_b32 v150, a48 offset:192
	ds_write_b32 v150, a49 offset:464
	ds_write_b32 v150, a50 offset:736
	ds_write_b32 v150, a51 offset:1008
	ds_write_b32 v150, a44 offset:4352
	ds_write_b32 v150, a45 offset:4624
	ds_write_b32 v150, a46 offset:4896
	ds_write_b32 v150, a47 offset:5168
	ds_write_b32 v150, a40 offset:4416
	ds_write_b32 v150, a41 offset:4688
	ds_write_b32 v150, a42 offset:4960
	ds_write_b32 v150, a43 offset:5232
	ds_write_b32 v150, a36 offset:4480
	ds_write_b32 v150, a37 offset:4752
	ds_write_b32 v150, a38 offset:5024
	ds_write_b32 v150, a39 offset:5296
	ds_write_b32 v150, a32 offset:4544
	ds_write_b32 v150, a33 offset:4816
	ds_write_b32 v150, a34 offset:5088
	ds_write_b32 v150, a35 offset:5360
	ds_read_b128 v[68:71], v143
	s_waitcnt lgkmcnt(0)
	v_pk_fma_f32 v[64:65], v[0:1], v[68:69], v[64:65]
	v_add_co_u32_e32 v68, vcc, s88, v140
	v_pk_fma_f32 v[66:67], v[2:3], v[70:71], v[66:67]
	s_nop 0
	v_addc_co_u32_e32 v69, vcc, 0, v141, vcc
	v_mul_f32_e32 v186, v64, v64
	v_fmac_f32_e32 v186, v65, v65
	v_fmac_f32_e32 v186, v66, v66
	v_fmac_f32_e32 v186, v67, v67
	v_subrev_u32_e32 v187, s50, v68
	v_bfe_u32 v188, v187, 8, 4
	s_nop 1
	v_add_f32_dpp v186, v186, v186 row_ror:8 row_mask:0xf bank_mask:0xf
	s_nop 1
	v_add_f32_dpp v186, v186, v186 row_ror:4 row_mask:0xf bank_mask:0xf
	s_nop 1
	v_add_f32_dpp v186, v186, v186 row_ror:2 row_mask:0xf bank_mask:0xf
	s_nop 1
	v_add_f32_dpp v186, v186, v186 row_ror:1 row_mask:0xf bank_mask:0xf
	v_lshrrev_b32_e32 v187, 12, v187
	v_lshlrev_b32_e32 v187, 2, v187
	v_lshl_add_u32 v187, v188, s60, v187
	s_mov_b64 s[56:57], exec
	s_mov_b64 exec, s[58:59]
	global_store_dword v187, v186, s[52:53]
	s_mov_b64 exec, s[56:57]
	global_store_dwordx4 v[68:69], v[64:67], off nt
	ds_read_b128 v[64:67], v130
	s_waitcnt lgkmcnt(0)
	v_pk_fma_f32 v[60:61], v[0:1], v[64:65], v[60:61]
	v_add_co_u32_e32 v64, vcc, s88, v128
	v_pk_fma_f32 v[62:63], v[2:3], v[66:67], v[62:63]
	s_nop 0
	v_addc_co_u32_e32 v65, vcc, 0, v129, vcc
	v_mul_f32_e32 v186, v60, v60
	v_fmac_f32_e32 v186, v61, v61
	v_fmac_f32_e32 v186, v62, v62
	v_fmac_f32_e32 v186, v63, v63
	v_subrev_u32_e32 v187, s50, v64
	v_bfe_u32 v188, v187, 8, 4
	s_nop 1
	v_add_f32_dpp v186, v186, v186 row_ror:8 row_mask:0xf bank_mask:0xf
	s_nop 1
	v_add_f32_dpp v186, v186, v186 row_ror:4 row_mask:0xf bank_mask:0xf
	s_nop 1
	v_add_f32_dpp v186, v186, v186 row_ror:2 row_mask:0xf bank_mask:0xf
	s_nop 1
	v_add_f32_dpp v186, v186, v186 row_ror:1 row_mask:0xf bank_mask:0xf
	v_lshrrev_b32_e32 v187, 12, v187
	v_lshlrev_b32_e32 v187, 2, v187
	v_lshl_add_u32 v187, v188, s60, v187
	s_mov_b64 s[56:57], exec
	s_mov_b64 exec, s[58:59]
	global_store_dword v187, v186, s[52:53]
	s_mov_b64 exec, s[56:57]
	global_store_dwordx4 v[64:65], v[60:63], off nt
	ds_read_b128 v[60:63], v130 offset:1088
	s_waitcnt lgkmcnt(0)
; DI void gemm_out_phase(const Params& P, int l, char* smem) {
;     ...
;     {
;       float* stg = (float*)(smem + 98304 + wave2 * 12288);
; #pragma unroll
;       for (int q = 0; q < 4; q++) {
; #pragma unroll
;         for (int ml = 0; ml < 2; ml++)
; #pragma unroll
;           for (int nn = 0; nn < 4; nn++)
; #pragma unroll
;             for (int j = 0; j < 4; j++) stg[(ml * 16 + fq2 * 4 + j) * 68 + nn * 16 + fr2] = acc[q * 2 + ml][nn][j];
;         __builtin_amdgcn_wave_barrier();
; #pragma unroll
;         for (int i = 0; i < 8; i++) {
;           const int row = i * 4 + fq2;
;           const float4 a = *(const float4*)(stg + row * 68 + fr2 * 4);
;           float4 r = rres[q][i];
;           r.x += g4.x * a.x; r.y += g4.y * a.y; r.z += g4.z * a.z; r.w += g4.w * a.w;
;           *(float4*)(dst + (size_t)(q * 32 + row) * D) = r;
;         }
	v_pk_fma_f32 v[56:57], v[0:1], v[60:61], v[56:57]
	v_add_co_u32_e32 v60, vcc, s88, v124
	v_pk_fma_f32 v[58:59], v[2:3], v[62:63], v[58:59]
	s_nop 0
	v_addc_co_u32_e32 v61, vcc, 0, v125, vcc
	v_mul_f32_e32 v186, v56, v56
	v_fmac_f32_e32 v186, v57, v57
	v_fmac_f32_e32 v186, v58, v58
	v_fmac_f32_e32 v186, v59, v59
	v_subrev_u32_e32 v187, s50, v60
	v_bfe_u32 v188, v187, 8, 4
	s_nop 1
	v_add_f32_dpp v186, v186, v186 row_ror:8 row_mask:0xf bank_mask:0xf
	s_nop 1
	v_add_f32_dpp v186, v186, v186 row_ror:4 row_mask:0xf bank_mask:0xf
	s_nop 1
	v_add_f32_dpp v186, v186, v186 row_ror:2 row_mask:0xf bank_mask:0xf
	s_nop 1
	v_add_f32_dpp v186, v186, v186 row_ror:1 row_mask:0xf bank_mask:0xf
	v_lshrrev_b32_e32 v187, 12, v187
	v_lshlrev_b32_e32 v187, 2, v187
	v_lshl_add_u32 v187, v188, s60, v187
	s_mov_b64 s[56:57], exec
	s_mov_b64 exec, s[58:59]
	global_store_dword v187, v186, s[52:53]
	s_mov_b64 exec, s[56:57]
	global_store_dwordx4 v[60:61], v[56:59], off nt
	ds_read_b128 v[56:59], v130 offset:2176
	s_waitcnt lgkmcnt(0)
	v_pk_fma_f32 v[52:53], v[0:1], v[56:57], v[52:53]
	v_add_co_u32_e32 v56, vcc, s88, v120
	v_pk_fma_f32 v[54:55], v[2:3], v[58:59], v[54:55]
	s_nop 0
	v_addc_co_u32_e32 v57, vcc, 0, v121, vcc
	v_mul_f32_e32 v186, v52, v52
	v_fmac_f32_e32 v186, v53, v53
	v_fmac_f32_e32 v186, v54, v54
	v_fmac_f32_e32 v186, v55, v55
	v_subrev_u32_e32 v187, s50, v56
	v_bfe_u32 v188, v187, 8, 4
	s_nop 1
	v_add_f32_dpp v186, v186, v186 row_ror:8 row_mask:0xf bank_mask:0xf
	s_nop 1
	v_add_f32_dpp v186, v186, v186 row_ror:4 row_mask:0xf bank_mask:0xf
	s_nop 1
	v_add_f32_dpp v186, v186, v186 row_ror:2 row_mask:0xf bank_mask:0xf
	s_nop 1
	v_add_f32_dpp v186, v186, v186 row_ror:1 row_mask:0xf bank_mask:0xf
	v_lshrrev_b32_e32 v187, 12, v187
	v_lshlrev_b32_e32 v187, 2, v187
	v_lshl_add_u32 v187, v188, s60, v187
	s_mov_b64 s[56:57], exec
	s_mov_b64 exec, s[58:59]
	global_store_dword v187, v186, s[52:53]
	s_mov_b64 exec, s[56:57]
	global_store_dwordx4 v[56:57], v[52:55], off nt
	ds_read_b128 v[52:55], v130 offset:3264
	s_waitcnt lgkmcnt(0)
	v_pk_fma_f32 v[48:49], v[0:1], v[52:53], v[48:49]
	v_add_co_u32_e32 v52, vcc, s88, v116
	v_pk_fma_f32 v[50:51], v[2:3], v[54:55], v[50:51]
	s_nop 0
	v_addc_co_u32_e32 v53, vcc, 0, v117, vcc
	v_mul_f32_e32 v186, v48, v48
	v_fmac_f32_e32 v186, v49, v49
	v_fmac_f32_e32 v186, v50, v50
	v_fmac_f32_e32 v186, v51, v51
	v_subrev_u32_e32 v187, s50, v52
	v_bfe_u32 v188, v187, 8, 4
	s_nop 1
	v_add_f32_dpp v186, v186, v186 row_ror:8 row_mask:0xf bank_mask:0xf
	s_nop 1
	v_add_f32_dpp v186, v186, v186 row_ror:4 row_mask:0xf bank_mask:0xf
	s_nop 1
	v_add_f32_dpp v186, v186, v186 row_ror:2 row_mask:0xf bank_mask:0xf
	s_nop 1
	v_add_f32_dpp v186, v186, v186 row_ror:1 row_mask:0xf bank_mask:0xf
	v_lshrrev_b32_e32 v187, 12, v187
	v_lshlrev_b32_e32 v187, 2, v187
	v_lshl_add_u32 v187, v188, s60, v187
	s_mov_b64 s[56:57], exec
	s_mov_b64 exec, s[58:59]
	global_store_dword v187, v186, s[52:53]
	s_mov_b64 exec, s[56:57]
	global_store_dwordx4 v[52:53], v[48:51], off nt
	ds_read_b128 v[48:51], v130 offset:4352
	s_waitcnt lgkmcnt(0)
	v_pk_fma_f32 v[44:45], v[0:1], v[48:49], v[44:45]
	v_add_co_u32_e32 v48, vcc, s88, v112
	v_pk_fma_f32 v[46:47], v[2:3], v[50:51], v[46:47]
	s_nop 0
	v_addc_co_u32_e32 v49, vcc, 0, v113, vcc
	v_mul_f32_e32 v186, v44, v44
	v_fmac_f32_e32 v186, v45, v45
	v_fmac_f32_e32 v186, v46, v46
	v_fmac_f32_e32 v186, v47, v47
	v_subrev_u32_e32 v187, s50, v48
	v_bfe_u32 v188, v187, 8, 4
	s_nop 1
	v_add_f32_dpp v186, v186, v186 row_ror:8 row_mask:0xf bank_mask:0xf
	s_nop 1
	v_add_f32_dpp v186, v186, v186 row_ror:4 row_mask:0xf bank_mask:0xf
	s_nop 1
	v_add_f32_dpp v186, v186, v186 row_ror:2 row_mask:0xf bank_mask:0xf
	s_nop 1
	v_add_f32_dpp v186, v186, v186 row_ror:1 row_mask:0xf bank_mask:0xf
	v_lshrrev_b32_e32 v187, 12, v187
	v_lshlrev_b32_e32 v187, 2, v187
	v_lshl_add_u32 v187, v188, s60, v187
	s_mov_b64 s[56:57], exec
	s_mov_b64 exec, s[58:59]
	global_store_dword v187, v186, s[52:53]
	s_mov_b64 exec, s[56:57]
	global_store_dwordx4 v[48:49], v[44:47], off nt
	ds_read_b128 v[44:47], v130 offset:5440
	s_waitcnt lgkmcnt(0)
	v_pk_fma_f32 v[40:41], v[0:1], v[44:45], v[40:41]
	v_add_co_u32_e32 v44, vcc, s88, v108
	v_pk_fma_f32 v[42:43], v[2:3], v[46:47], v[42:43]
	s_nop 0
	v_addc_co_u32_e32 v45, vcc, 0, v109, vcc
	v_mul_f32_e32 v186, v40, v40
	v_fmac_f32_e32 v186, v41, v41
	v_fmac_f32_e32 v186, v42, v42
	v_fmac_f32_e32 v186, v43, v43
	v_subrev_u32_e32 v187, s50, v44
	v_bfe_u32 v188, v187, 8, 4
	s_nop 1
	v_add_f32_dpp v186, v186, v186 row_ror:8 row_mask:0xf bank_mask:0xf
	s_nop 1
	v_add_f32_dpp v186, v186, v186 row_ror:4 row_mask:0xf bank_mask:0xf
	s_nop 1
	v_add_f32_dpp v186, v186, v186 row_ror:2 row_mask:0xf bank_mask:0xf
	s_nop 1
	v_add_f32_dpp v186, v186, v186 row_ror:1 row_mask:0xf bank_mask:0xf
	v_lshrrev_b32_e32 v187, 12, v187
	v_lshlrev_b32_e32 v187, 2, v187
	v_lshl_add_u32 v187, v188, s60, v187
	s_mov_b64 s[56:57], exec
	s_mov_b64 exec, s[58:59]
	global_store_dword v187, v186, s[52:53]
	s_mov_b64 exec, s[56:57]
	global_store_dwordx4 v[44:45], v[40:43], off nt
	ds_read_b128 v[40:43], v130 offset:6528
	s_waitcnt lgkmcnt(0)
; DI void gemm_out_phase(const Params& P, int l, char* smem) {
;     ...
;     {
;       float* stg = (float*)(smem + 98304 + wave2 * 12288);
; #pragma unroll
;       for (int q = 0; q < 4; q++) {
; #pragma unroll
;         for (int ml = 0; ml < 2; ml++)
; #pragma unroll
;           for (int nn = 0; nn < 4; nn++)
; #pragma unroll
;             for (int j = 0; j < 4; j++) stg[(ml * 16 + fq2 * 4 + j) * 68 + nn * 16 + fr2] = acc[q * 2 + ml][nn][j];
;         __builtin_amdgcn_wave_barrier();
; #pragma unroll
;         for (int i = 0; i < 8; i++) {
;           const int row = i * 4 + fq2;
;           const float4 a = *(const float4*)(stg + row * 68 + fr2 * 4);
;           float4 r = rres[q][i];
;           r.x += g4.x * a.x; r.y += g4.y * a.y; r.z += g4.z * a.z; r.w += g4.w * a.w;
;           *(float4*)(dst + (size_t)(q * 32 + row) * D) = r;
;         }
	v_pk_fma_f32 v[36:37], v[0:1], v[40:41], v[36:37]
	v_add_co_u32_e32 v40, vcc, s88, v104
	v_pk_fma_f32 v[38:39], v[2:3], v[42:43], v[38:39]
	s_nop 0
	v_addc_co_u32_e32 v41, vcc, 0, v105, vcc
	v_mul_f32_e32 v186, v36, v36
	v_fmac_f32_e32 v186, v37, v37
	v_fmac_f32_e32 v186, v38, v38
	v_fmac_f32_e32 v186, v39, v39
	v_subrev_u32_e32 v187, s50, v40
	v_bfe_u32 v188, v187, 8, 4
	s_nop 1
	v_add_f32_dpp v186, v186, v186 row_ror:8 row_mask:0xf bank_mask:0xf
	s_nop 1
	v_add_f32_dpp v186, v186, v186 row_ror:4 row_mask:0xf bank_mask:0xf
	s_nop 1
	v_add_f32_dpp v186, v186, v186 row_ror:2 row_mask:0xf bank_mask:0xf
	s_nop 1
	v_add_f32_dpp v186, v186, v186 row_ror:1 row_mask:0xf bank_mask:0xf
	v_lshrrev_b32_e32 v187, 12, v187
	v_lshlrev_b32_e32 v187, 2, v187
	v_lshl_add_u32 v187, v188, s60, v187
	s_mov_b64 s[56:57], exec
	s_mov_b64 exec, s[58:59]
	global_store_dword v187, v186, s[52:53]
	s_mov_b64 exec, s[56:57]
	global_store_dwordx4 v[40:41], v[36:39], off nt
	ds_write_b32 v150, a28
	ds_write_b32 v150, a29 offset:272
	ds_write_b32 v150, a30 offset:544
	ds_write_b32 v150, a31 offset:816
	ds_write_b32 v150, a24 offset:64
	ds_write_b32 v150, a25 offset:336
	ds_write_b32 v150, a26 offset:608
	ds_write_b32 v150, a27 offset:880
	ds_write_b32 v150, a20 offset:128
	ds_write_b32 v150, a21 offset:400
	ds_write_b32 v150, a22 offset:672
	ds_write_b32 v150, a23 offset:944
	ds_write_b32 v150, a16 offset:192
	ds_write_b32 v150, a17 offset:464
	ds_write_b32 v150, a18 offset:736
	ds_write_b32 v150, a19 offset:1008
	ds_write_b32 v150, a8 offset:4352
	ds_write_b32 v150, a9 offset:4624
	ds_write_b32 v150, a10 offset:4896
	ds_write_b32 v150, a11 offset:5168
	ds_write_b32 v150, a0 offset:4416
	ds_write_b32 v150, a1 offset:4688
	ds_write_b32 v150, a2 offset:4960
	ds_write_b32 v150, a3 offset:5232
	ds_write_b32 v150, a4 offset:4480
	ds_write_b32 v150, a5 offset:4752
	ds_write_b32 v150, a6 offset:5024
	ds_write_b32 v150, a7 offset:5296
	ds_write_b32 v150, a12 offset:4544
	ds_write_b32 v150, a13 offset:4816
	ds_write_b32 v150, a14 offset:5088
	ds_write_b32 v150, a15 offset:5360
	ds_read_b128 v[36:39], v143
	s_waitcnt lgkmcnt(0)
	v_pk_fma_f32 v[32:33], v[0:1], v[36:37], v[32:33]
	v_add_co_u32_e32 v36, vcc, s2, v140
	v_pk_fma_f32 v[34:35], v[2:3], v[38:39], v[34:35]
	s_nop 0
	v_addc_co_u32_e32 v37, vcc, 0, v141, vcc
	v_mul_f32_e32 v186, v32, v32
	v_fmac_f32_e32 v186, v33, v33
	v_fmac_f32_e32 v186, v34, v34
	v_fmac_f32_e32 v186, v35, v35
	v_subrev_u32_e32 v187, s50, v36
	v_bfe_u32 v188, v187, 8, 4
	s_nop 1
	v_add_f32_dpp v186, v186, v186 row_ror:8 row_mask:0xf bank_mask:0xf
	s_nop 1
	v_add_f32_dpp v186, v186, v186 row_ror:4 row_mask:0xf bank_mask:0xf
	s_nop 1
	v_add_f32_dpp v186, v186, v186 row_ror:2 row_mask:0xf bank_mask:0xf
	s_nop 1
	v_add_f32_dpp v186, v186, v186 row_ror:1 row_mask:0xf bank_mask:0xf
	v_lshrrev_b32_e32 v187, 12, v187
	v_lshlrev_b32_e32 v187, 2, v187
	v_lshl_add_u32 v187, v188, s60, v187
	s_mov_b64 s[56:57], exec
	s_mov_b64 exec, s[58:59]
	global_store_dword v187, v186, s[52:53]
	s_mov_b64 exec, s[56:57]
	global_store_dwordx4 v[36:37], v[32:35], off nt
	ds_read_b128 v[32:35], v130
	s_waitcnt lgkmcnt(0)
	v_pk_fma_f32 v[28:29], v[0:1], v[32:33], v[28:29]
	v_add_co_u32_e32 v32, vcc, s2, v128
	v_pk_fma_f32 v[30:31], v[2:3], v[34:35], v[30:31]
	s_nop 0
	v_addc_co_u32_e32 v33, vcc, 0, v129, vcc
	v_mul_f32_e32 v186, v28, v28
	v_fmac_f32_e32 v186, v29, v29
	v_fmac_f32_e32 v186, v30, v30
	v_fmac_f32_e32 v186, v31, v31
	v_subrev_u32_e32 v187, s50, v32
	v_bfe_u32 v188, v187, 8, 4
	s_nop 1
	v_add_f32_dpp v186, v186, v186 row_ror:8 row_mask:0xf bank_mask:0xf
	s_nop 1
	v_add_f32_dpp v186, v186, v186 row_ror:4 row_mask:0xf bank_mask:0xf
	s_nop 1
	v_add_f32_dpp v186, v186, v186 row_ror:2 row_mask:0xf bank_mask:0xf
	s_nop 1
	v_add_f32_dpp v186, v186, v186 row_ror:1 row_mask:0xf bank_mask:0xf
	v_lshrrev_b32_e32 v187, 12, v187
	v_lshlrev_b32_e32 v187, 2, v187
	v_lshl_add_u32 v187, v188, s60, v187
	s_mov_b64 s[56:57], exec
	s_mov_b64 exec, s[58:59]
	global_store_dword v187, v186, s[52:53]
	s_mov_b64 exec, s[56:57]
	global_store_dwordx4 v[32:33], v[28:31], off nt
	ds_read_b128 v[28:31], v130 offset:1088
	s_waitcnt lgkmcnt(0)
	v_pk_fma_f32 v[24:25], v[0:1], v[28:29], v[24:25]
	v_add_co_u32_e32 v28, vcc, s2, v124
	v_pk_fma_f32 v[26:27], v[2:3], v[30:31], v[26:27]
	s_nop 0
	v_addc_co_u32_e32 v29, vcc, 0, v125, vcc
	v_mul_f32_e32 v186, v24, v24
	v_fmac_f32_e32 v186, v25, v25
	v_fmac_f32_e32 v186, v26, v26
	v_fmac_f32_e32 v186, v27, v27
	v_subrev_u32_e32 v187, s50, v28
	v_bfe_u32 v188, v187, 8, 4
	s_nop 1
	v_add_f32_dpp v186, v186, v186 row_ror:8 row_mask:0xf bank_mask:0xf
	s_nop 1
	v_add_f32_dpp v186, v186, v186 row_ror:4 row_mask:0xf bank_mask:0xf
	s_nop 1
	v_add_f32_dpp v186, v186, v186 row_ror:2 row_mask:0xf bank_mask:0xf
	s_nop 1
	v_add_f32_dpp v186, v186, v186 row_ror:1 row_mask:0xf bank_mask:0xf
	v_lshrrev_b32_e32 v187, 12, v187
	v_lshlrev_b32_e32 v187, 2, v187
	v_lshl_add_u32 v187, v188, s60, v187
	s_mov_b64 s[56:57], exec
	s_mov_b64 exec, s[58:59]
	global_store_dword v187, v186, s[52:53]
	s_mov_b64 exec, s[56:57]
	global_store_dwordx4 v[28:29], v[24:27], off nt
	ds_read_b128 v[24:27], v130 offset:2176
	s_waitcnt lgkmcnt(0)
; DI void gemm_out_phase(const Params& P, int l, char* smem) {
;     ...
;     {
;       float* stg = (float*)(smem + 98304 + wave2 * 12288);
; #pragma unroll
;       for (int q = 0; q < 4; q++) {
; #pragma unroll
;         for (int ml = 0; ml < 2; ml++)
; #pragma unroll
;           for (int nn = 0; nn < 4; nn++)
; #pragma unroll
;             for (int j = 0; j < 4; j++) stg[(ml * 16 + fq2 * 4 + j) * 68 + nn * 16 + fr2] = acc[q * 2 + ml][nn][j];
;         __builtin_amdgcn_wave_barrier();
; #pragma unroll
;         for (int i = 0; i < 8; i++) {
;           const int row = i * 4 + fq2;
;           const float4 a = *(const float4*)(stg + row * 68 + fr2 * 4);
;           float4 r = rres[q][i];
;           r.x += g4.x * a.x; r.y += g4.y * a.y; r.z += g4.z * a.z; r.w += g4.w * a.w;
;           *(float4*)(dst + (size_t)(q * 32 + row) * D) = r;
;         }
;         __builtin_amdgcn_wave_barrier();
;       }
;     }
;     mt = mt2; nt = nt2; it = it2; have = have2; a0 = a1; b0 = b1;
	v_pk_fma_f32 v[20:21], v[0:1], v[24:25], v[20:21]
	v_add_co_u32_e32 v24, vcc, s2, v120
	v_pk_fma_f32 v[22:23], v[2:3], v[26:27], v[22:23]
	s_nop 0
	v_addc_co_u32_e32 v25, vcc, 0, v121, vcc
	v_mul_f32_e32 v186, v20, v20
	v_fmac_f32_e32 v186, v21, v21
	v_fmac_f32_e32 v186, v22, v22
	v_fmac_f32_e32 v186, v23, v23
	v_subrev_u32_e32 v187, s50, v24
	v_bfe_u32 v188, v187, 8, 4
	s_nop 1
	v_add_f32_dpp v186, v186, v186 row_ror:8 row_mask:0xf bank_mask:0xf
	s_nop 1
	v_add_f32_dpp v186, v186, v186 row_ror:4 row_mask:0xf bank_mask:0xf
	s_nop 1
	v_add_f32_dpp v186, v186, v186 row_ror:2 row_mask:0xf bank_mask:0xf
	s_nop 1
	v_add_f32_dpp v186, v186, v186 row_ror:1 row_mask:0xf bank_mask:0xf
	v_lshrrev_b32_e32 v187, 12, v187
	v_lshlrev_b32_e32 v187, 2, v187
	v_lshl_add_u32 v187, v188, s60, v187
	s_mov_b64 s[56:57], exec
	s_mov_b64 exec, s[58:59]
	global_store_dword v187, v186, s[52:53]
	s_mov_b64 exec, s[56:57]
	global_store_dwordx4 v[24:25], v[20:23], off nt
	ds_read_b128 v[20:23], v130 offset:3264
	s_waitcnt lgkmcnt(0)
	v_pk_fma_f32 v[16:17], v[0:1], v[20:21], v[16:17]
	v_add_co_u32_e32 v20, vcc, s2, v116
	v_pk_fma_f32 v[18:19], v[2:3], v[22:23], v[18:19]
	s_nop 0
	v_addc_co_u32_e32 v21, vcc, 0, v117, vcc
	v_mul_f32_e32 v186, v16, v16
	v_fmac_f32_e32 v186, v17, v17
	v_fmac_f32_e32 v186, v18, v18
	v_fmac_f32_e32 v186, v19, v19
	v_subrev_u32_e32 v187, s50, v20
	v_bfe_u32 v188, v187, 8, 4
	s_nop 1
	v_add_f32_dpp v186, v186, v186 row_ror:8 row_mask:0xf bank_mask:0xf
	s_nop 1
	v_add_f32_dpp v186, v186, v186 row_ror:4 row_mask:0xf bank_mask:0xf
	s_nop 1
	v_add_f32_dpp v186, v186, v186 row_ror:2 row_mask:0xf bank_mask:0xf
	s_nop 1
	v_add_f32_dpp v186, v186, v186 row_ror:1 row_mask:0xf bank_mask:0xf
	v_lshrrev_b32_e32 v187, 12, v187
	v_lshlrev_b32_e32 v187, 2, v187
	v_lshl_add_u32 v187, v188, s60, v187
	s_mov_b64 s[56:57], exec
	s_mov_b64 exec, s[58:59]
	global_store_dword v187, v186, s[52:53]
	s_mov_b64 exec, s[56:57]
	global_store_dwordx4 v[20:21], v[16:19], off nt
	ds_read_b128 v[16:19], v130 offset:4352
	s_waitcnt lgkmcnt(0)
	v_pk_fma_f32 v[12:13], v[0:1], v[16:17], v[12:13]
	v_add_co_u32_e32 v16, vcc, s2, v112
	v_pk_fma_f32 v[14:15], v[2:3], v[18:19], v[14:15]
	s_nop 0
	v_addc_co_u32_e32 v17, vcc, 0, v113, vcc
	v_mul_f32_e32 v186, v12, v12
	v_fmac_f32_e32 v186, v13, v13
	v_fmac_f32_e32 v186, v14, v14
	v_fmac_f32_e32 v186, v15, v15
	v_subrev_u32_e32 v187, s50, v16
	v_bfe_u32 v188, v187, 8, 4
	s_nop 1
	v_add_f32_dpp v186, v186, v186 row_ror:8 row_mask:0xf bank_mask:0xf
	s_nop 1
	v_add_f32_dpp v186, v186, v186 row_ror:4 row_mask:0xf bank_mask:0xf
	s_nop 1
	v_add_f32_dpp v186, v186, v186 row_ror:2 row_mask:0xf bank_mask:0xf
	s_nop 1
	v_add_f32_dpp v186, v186, v186 row_ror:1 row_mask:0xf bank_mask:0xf
	v_lshrrev_b32_e32 v187, 12, v187
	v_lshlrev_b32_e32 v187, 2, v187
	v_lshl_add_u32 v187, v188, s60, v187
	s_mov_b64 s[56:57], exec
	s_mov_b64 exec, s[58:59]
	global_store_dword v187, v186, s[52:53]
	s_mov_b64 exec, s[56:57]
	global_store_dwordx4 v[16:17], v[12:15], off nt
	ds_read_b128 v[12:15], v130 offset:5440
	s_waitcnt lgkmcnt(0)
	v_pk_fma_f32 v[8:9], v[0:1], v[12:13], v[8:9]
	v_add_co_u32_e32 v12, vcc, s2, v108
	v_pk_fma_f32 v[10:11], v[2:3], v[14:15], v[10:11]
	s_nop 0
	v_addc_co_u32_e32 v13, vcc, 0, v109, vcc
	v_mul_f32_e32 v186, v8, v8
	v_fmac_f32_e32 v186, v9, v9
	v_fmac_f32_e32 v186, v10, v10
	v_fmac_f32_e32 v186, v11, v11
	v_subrev_u32_e32 v187, s50, v12
	v_bfe_u32 v188, v187, 8, 4
	s_nop 1
	v_add_f32_dpp v186, v186, v186 row_ror:8 row_mask:0xf bank_mask:0xf
	s_nop 1
	v_add_f32_dpp v186, v186, v186 row_ror:4 row_mask:0xf bank_mask:0xf
	s_nop 1
	v_add_f32_dpp v186, v186, v186 row_ror:2 row_mask:0xf bank_mask:0xf
	s_nop 1
	v_add_f32_dpp v186, v186, v186 row_ror:1 row_mask:0xf bank_mask:0xf
	v_lshrrev_b32_e32 v187, 12, v187
	v_lshlrev_b32_e32 v187, 2, v187
	v_lshl_add_u32 v187, v188, s60, v187
	s_mov_b64 s[56:57], exec
	s_mov_b64 exec, s[58:59]
	global_store_dword v187, v186, s[52:53]
	s_mov_b64 exec, s[56:57]
	global_store_dwordx4 v[12:13], v[8:11], off nt
	ds_read_b128 v[8:11], v130 offset:6528
	s_waitcnt lgkmcnt(0)
	v_pk_fma_f32 v[0:1], v[0:1], v[8:9], v[4:5]
	v_add_co_u32_e32 v4, vcc, 0x60000, v104
	v_pk_fma_f32 v[2:3], v[2:3], v[10:11], v[6:7]
	s_nop 0
	v_addc_co_u32_e32 v5, vcc, 0, v105, vcc
	s_andn2_b64 vcc, exec, s[0:1]
	v_mul_f32_e32 v186, v0, v0
	v_fmac_f32_e32 v186, v1, v1
	v_fmac_f32_e32 v186, v2, v2
	v_fmac_f32_e32 v186, v3, v3
	v_subrev_u32_e32 v187, s50, v4
	v_bfe_u32 v188, v187, 8, 4
	s_nop 1
	v_add_f32_dpp v186, v186, v186 row_ror:8 row_mask:0xf bank_mask:0xf
	s_nop 1
	v_add_f32_dpp v186, v186, v186 row_ror:4 row_mask:0xf bank_mask:0xf
	s_nop 1
	v_add_f32_dpp v186, v186, v186 row_ror:2 row_mask:0xf bank_mask:0xf
	s_nop 1
	v_add_f32_dpp v186, v186, v186 row_ror:1 row_mask:0xf bank_mask:0xf
	v_lshrrev_b32_e32 v187, 12, v187
	v_lshlrev_b32_e32 v187, 2, v187
	v_lshl_add_u32 v187, v188, s60, v187
	s_mov_b64 s[56:57], exec
	s_mov_b64 exec, s[58:59]
	global_store_dword v187, v186, s[52:53]
	s_mov_b64 exec, s[56:57]
	global_store_dwordx4 v[4:5], v[0:3], off nt
	s_cbranch_vccz .LBB0_533

; DI void moe_e2_phase(const Params& P, int l, char* smem, int* tb) {
;     ...
; #pragma unroll
;       for (int h = 0; h < 2; h++) {
; #pragma unroll
;         for (int ml = 0; ml < 4; ml++)
; #pragma unroll
;           for (int n = 0; n < 4; n++)
; #pragma unroll
;             for (int j = 0; j < 4; j++) stage_put(stg, ml, n, j, fr2, fq2, acc[h * 4 + ml][n][j]);
;         __builtin_amdgcn_wave_barrier();
; #pragma unroll
;         for (int i = 0; i < 8; i++) {
;           const int c = i * 64 + lane2, row = c >> 3, c16 = c & 7;
;           h8 v = *(const h8*)(stg + row * 144 + c16 * 16);
;           if (aa[h][i] >= 0) {
;             const float w = ww[h][i];
; #pragma unroll
;             for (int u = 0; u < 8; u++) v[u] = (half_t)(w * (float)v[u]);
;             *(h8*)(P.yA + (size_t)aa[h][i] * D + nt * 128 + wc2 * 64 + c16 * 8) = v;
.LBB0_631:
	v_lshrrev_b32_e32 v14, 6, v87
	s_movk_i32 s1, 0x3000
	v_mul_lo_u32 v14, v14, s1
	v_cmp_lt_i32_e32 vcc, v88, v33
	v_add_u32_e32 v88, 0x18000, v14
	v_lshrrev_b32_e32 v14, 2, v87
	s_waitcnt vmcnt(0)
	v_cndmask_b32_e32 v4, -1, v89, vcc
	v_and_b32_e32 v89, 12, v14
	v_lshlrev_b32_e32 v14, 1, v87
	v_and_b32_e32 v156, 30, v14
	v_and_b32_e32 v157, 7, v87
	v_cvt_f16_f32_e32 v158, v6
	v_mul_u32_u24_e32 v6, 0x90, v89
	v_lshl_or_b32 v14, v157, 4, v88
	v_or3_b32 v6, v88, v156, v6
	v_cvt_f16_f32_e32 v88, v204
	v_cvt_f16_f32_e32 v89, v203
	v_cvt_f16_f32_e32 v156, v205
	ds_write_b16 v6, v158
	ds_write_b16 v6, v88 offset:144
	ds_write_b16 v6, v89 offset:288
	ds_write_b16 v6, v156 offset:432
	v_cvt_f16_f32_e32 v88, v202
	v_cvt_f16_f32_e32 v89, v201
	v_cvt_f16_f32_e32 v156, v200
	v_cvt_f16_f32_e32 v158, v199
	ds_write_b16 v6, v88 offset:32
	ds_write_b16 v6, v89 offset:176
	ds_write_b16 v6, v156 offset:320
	ds_write_b16 v6, v158 offset:464
	v_cvt_f16_f32_e32 v88, v198
	v_cvt_f16_f32_e32 v89, v197
	v_cvt_f16_f32_e32 v156, v196
	v_cvt_f16_f32_e32 v158, v195
	ds_write_b16 v6, v88 offset:64
	ds_write_b16 v6, v89 offset:208
	ds_write_b16 v6, v156 offset:352
	ds_write_b16 v6, v158 offset:496
	v_cvt_f16_f32_e32 v88, v194
	v_cvt_f16_f32_e32 v89, v193
	v_cvt_f16_f32_e32 v156, v192
	v_cvt_f16_f32_e32 v158, v191
	ds_write_b16 v6, v88 offset:96
	ds_write_b16 v6, v89 offset:240
	ds_write_b16 v6, v156 offset:384
	ds_write_b16 v6, v158 offset:528
	v_cvt_f16_f32_e32 v88, v190
	v_cvt_f16_f32_e32 v89, v189
	v_cvt_f16_f32_e32 v156, v188
	v_cvt_f16_f32_e32 v158, v187
	ds_write_b16 v6, v88 offset:2304
	ds_write_b16 v6, v89 offset:2448
	ds_write_b16 v6, v156 offset:2592
	ds_write_b16 v6, v158 offset:2736
	v_cvt_f16_f32_e32 v88, v186
	v_cvt_f16_f32_e32 v89, v185
	v_cvt_f16_f32_e32 v156, v184
	v_cvt_f16_f32_e32 v158, v183
	ds_write_b16 v6, v88 offset:2336
	ds_write_b16 v6, v89 offset:2480
	ds_write_b16 v6, v156 offset:2624
	ds_write_b16 v6, v158 offset:2768
	v_cvt_f16_f32_e32 v88, v182
	v_cvt_f16_f32_e32 v89, v181
	v_cvt_f16_f32_e32 v156, v180
	v_cvt_f16_f32_e32 v158, v179
	ds_write_b16 v6, v88 offset:2368
	ds_write_b16 v6, v89 offset:2512
	ds_write_b16 v6, v156 offset:2656
	ds_write_b16 v6, v158 offset:2800
	v_cvt_f16_f32_e32 v88, v176
	v_cvt_f16_f32_e32 v89, v175
	v_cvt_f16_f32_e32 v156, v174
	v_cvt_f16_f32_e32 v158, v173
	ds_write_b16 v6, v88 offset:2400
	ds_write_b16 v6, v89 offset:2544
	ds_write_b16 v6, v156 offset:2688
	ds_write_b16 v6, v158 offset:2832
	v_cvt_f16_f32_e32 v88, v171
	v_cvt_f16_f32_e32 v18, v18
	v_cvt_f16_f32_e32 v9, v9
	v_cvt_f16_f32_e32 v89, v170
	v_cvt_f16_f32_e32 v17, v17
	v_cvt_f16_f32_e32 v8, v8
	v_cvt_f16_f32_e32 v23, v23
	v_cvt_f16_f32_e32 v11, v11
	v_cvt_f16_f32_e32 v3, v3
	v_cvt_f16_f32_e32 v19, v19
	v_cvt_f16_f32_e32 v10, v10
	v_cvt_f16_f32_e32 v2, v2
	ds_write_b16 v6, v88 offset:4608
	ds_write_b16 v6, v89 offset:4752
	ds_write_b16 v6, v23 offset:4896
	ds_write_b16 v6, v19 offset:5040
	ds_write_b16 v6, v18 offset:4640
	ds_write_b16 v6, v17 offset:4784
	ds_write_b16 v6, v11 offset:4928
	ds_write_b16 v6, v10 offset:5072
	ds_write_b16 v6, v9 offset:4672
	ds_write_b16 v6, v8 offset:4816
	ds_write_b16 v6, v3 offset:4960
	ds_write_b16 v6, v2 offset:5104
	v_cvt_f16_f32_e32 v2, v16
	v_cvt_f16_f32_e32 v3, v15
	v_cvt_f16_f32_e32 v1, v1
	v_cvt_f16_f32_e32 v0, v0
	ds_write_b16 v6, v2 offset:4704
	ds_write_b16 v6, v3 offset:4848
	ds_write_b16 v6, v1 offset:4992
	ds_write_b16 v6, v0 offset:5136
	v_cvt_f16_f32_e32 v0, v13
	v_cvt_f16_f32_e32 v1, v12
	v_cvt_f16_f32_e32 v2, v5
	v_cvt_f16_f32_e32 v3, v7
	ds_write_b16 v6, v0 offset:6912
	ds_write_b16 v6, v1 offset:7056
	ds_write_b16 v6, v2 offset:7200
	ds_write_b16 v6, v3 offset:7344
	v_cvt_f16_f32_e32 v0, v169
	v_cvt_f16_f32_e32 v1, v22
	v_cvt_f16_f32_e32 v2, v21
	v_cvt_f16_f32_e32 v3, v20
	ds_write_b16 v6, v0 offset:6944
	ds_write_b16 v6, v1 offset:7088
	ds_write_b16 v6, v2 offset:7232
	ds_write_b16 v6, v3 offset:7376
	v_cvt_f16_f32_e32 v0, v168
	v_cvt_f16_f32_e32 v1, v166
	v_cvt_f16_f32_e32 v2, v167
	v_cvt_f16_f32_e32 v3, v165
	ds_write_b16 v6, v0 offset:6976
	ds_write_b16 v6, v1 offset:7120
	ds_write_b16 v6, v2 offset:7264
	ds_write_b16 v6, v3 offset:7408
	v_cvt_f16_f32_e32 v0, v164
	v_cvt_f16_f32_e32 v1, v163
	v_cvt_f16_f32_e32 v2, v161
	s_lshl_b32 s4, s6, 7
	v_and_b32_e32 v87, 64, v87
	v_lshlrev_b32_e32 v157, 3, v157
	v_cvt_f16_f32_e32 v3, v162
	s_ashr_i32 s5, s4, 31
	ds_write_b16 v6, v0 offset:7008
	ds_write_b16 v6, v1 offset:7152
	ds_write_b16 v6, v2 offset:7296
	ds_write_b16 v6, v3 offset:7440
	v_cmp_lt_i32_e32 vcc, -1, v4
	v_mad_u32_u24 v7, v86, s40, v14
	v_lshlrev_b32_e32 v2, 1, v87
	v_lshlrev_b32_e32 v0, 1, v157
	s_and_saveexec_b64 s[6:7], vcc
	s_cbranch_execz .LBB0_633
	ds_read_b128 v[8:11], v7
	v_mov_b32_e32 v5, v149
	v_lshlrev_b64 v[4:5], 11, v[4:5]
	v_lshl_add_u64 v[4:5], s[18:19], 0, v[4:5]
	v_lshl_add_u64 v[4:5], s[4:5], 1, v[4:5]
	s_waitcnt lgkmcnt(0)
	v_cvt_f32_f16_e32 v12, v8
	v_cvt_f32_f16_sdwa v13, v8 dst_sel:DWORD dst_unused:UNUSED_PAD src0_sel:WORD_1
	v_mov_b32_e32 v3, v149
	v_lshl_add_u64 v[4:5], v[4:5], 0, v[2:3]
	v_mov_b32_e32 v1, v149
	v_pk_mul_f32 v[12:13], v[62:63], v[12:13] op_sel_hi:[0,1]
	v_cvt_pk_f16_f32 v8, v12, v13
	v_cvt_f32_f16_e32 v12, v9
	v_cvt_f32_f16_sdwa v13, v9 dst_sel:DWORD dst_unused:UNUSED_PAD src0_sel:WORD_1
	v_lshl_add_u64 v[4:5], v[4:5], 0, v[0:1]
	v_pk_mul_f32 v[12:13], v[62:63], v[12:13] op_sel_hi:[0,1]
	v_cvt_pk_f16_f32 v9, v12, v13
	v_cvt_f32_f16_e32 v12, v10
	v_cvt_f32_f16_sdwa v13, v10 dst_sel:DWORD dst_unused:UNUSED_PAD src0_sel:WORD_1
	v_pk_mul_f32 v[12:13], v[62:63], v[12:13] op_sel_hi:[0,1]
	v_cvt_pk_f16_f32 v10, v12, v13
	v_cvt_f32_f16_e32 v12, v11
	v_cvt_f32_f16_sdwa v13, v11 dst_sel:DWORD dst_unused:UNUSED_PAD src0_sel:WORD_1
	v_pk_mul_f32 v[12:13], v[62:63], v[12:13] op_sel_hi:[0,1]
	v_cvt_pk_f16_f32 v11, v12, v13
	global_store_dwordx4 v[4:5], v[8:11], off nt
; DI void moe_e2_phase(const Params& P, int l, char* smem, int* tb) {
;     ...
;         for (int i = 0; i < 8; i++) {
;           const int c = i * 64 + lane2, row = c >> 3, c16 = c & 7;
;           h8 v = *(const h8*)(stg + row * 144 + c16 * 16);
;           if (aa[h][i] >= 0) {
;             const float w = ww[h][i];
; #pragma unroll
;             for (int u = 0; u < 8; u++) v[u] = (half_t)(w * (float)v[u]);
;             *(h8*)(P.yA + (size_t)aa[h][i] * D + nt * 128 + wc2 * 64 + c16 * 8) = v;
;           }
;         }
.LBB0_633:
	s_or_b64 exec, exec, s[6:7]
	v_cmp_lt_i32_e32 vcc, v84, v33
	v_mad_u32_u24 v8, v83, s40, v14
	s_nop 0
	v_cndmask_b32_e32 v4, -1, v85, vcc
	v_cmp_lt_i32_e32 vcc, -1, v4
	s_and_saveexec_b64 s[6:7], vcc
	s_cbranch_execz .LBB0_635
	ds_read_b128 v[10:13], v8
	v_mov_b32_e32 v5, v149
	v_lshlrev_b64 v[4:5], 11, v[4:5]
	v_lshl_add_u64 v[4:5], s[18:19], 0, v[4:5]
	v_lshl_add_u64 v[4:5], s[4:5], 1, v[4:5]
	s_waitcnt lgkmcnt(0)
	v_cvt_f32_f16_e32 v16, v10
	v_cvt_f32_f16_sdwa v17, v10 dst_sel:DWORD dst_unused:UNUSED_PAD src0_sel:WORD_1
	v_mov_b32_e32 v3, v149
	v_lshl_add_u64 v[4:5], v[4:5], 0, v[2:3]
	v_mov_b32_e32 v1, v149
	v_pk_mul_f32 v[16:17], v[60:61], v[16:17] op_sel_hi:[0,1]
	v_cvt_pk_f16_f32 v10, v16, v17
	v_cvt_f32_f16_e32 v16, v11
	v_cvt_f32_f16_sdwa v17, v11 dst_sel:DWORD dst_unused:UNUSED_PAD src0_sel:WORD_1
	v_lshl_add_u64 v[4:5], v[4:5], 0, v[0:1]
	v_pk_mul_f32 v[16:17], v[60:61], v[16:17] op_sel_hi:[0,1]
	v_cvt_pk_f16_f32 v11, v16, v17
	v_cvt_f32_f16_e32 v16, v12
	v_cvt_f32_f16_sdwa v17, v12 dst_sel:DWORD dst_unused:UNUSED_PAD src0_sel:WORD_1
	v_pk_mul_f32 v[16:17], v[60:61], v[16:17] op_sel_hi:[0,1]
	v_cvt_pk_f16_f32 v12, v16, v17
	v_cvt_f32_f16_e32 v16, v13
	v_cvt_f32_f16_sdwa v17, v13 dst_sel:DWORD dst_unused:UNUSED_PAD src0_sel:WORD_1
	v_pk_mul_f32 v[16:17], v[60:61], v[16:17] op_sel_hi:[0,1]
	v_cvt_pk_f16_f32 v13, v16, v17
	global_store_dwordx4 v[4:5], v[10:13], off nt
.LBB0_635:
	s_or_b64 exec, exec, s[6:7]
	v_cmp_lt_i32_e32 vcc, v81, v33
	v_mad_u32_u24 v9, v80, s40, v14
	s_nop 0
	v_cndmask_b32_e32 v4, -1, v82, vcc
	v_cmp_lt_i32_e32 vcc, -1, v4
	s_and_saveexec_b64 s[6:7], vcc
	s_cbranch_execz .LBB0_637
	ds_read_b128 v[10:13], v9
	v_mov_b32_e32 v5, v149
	v_lshlrev_b64 v[4:5], 11, v[4:5]
	v_lshl_add_u64 v[4:5], s[18:19], 0, v[4:5]
	v_lshl_add_u64 v[4:5], s[4:5], 1, v[4:5]
	s_waitcnt lgkmcnt(0)
	v_cvt_f32_f16_e32 v16, v10
	v_cvt_f32_f16_sdwa v17, v10 dst_sel:DWORD dst_unused:UNUSED_PAD src0_sel:WORD_1
	v_mov_b32_e32 v3, v149
	v_lshl_add_u64 v[4:5], v[4:5], 0, v[2:3]
	v_mov_b32_e32 v1, v149
	v_pk_mul_f32 v[16:17], v[58:59], v[16:17] op_sel_hi:[0,1]
	v_cvt_pk_f16_f32 v10, v16, v17
	v_cvt_f32_f16_e32 v16, v11
	v_cvt_f32_f16_sdwa v17, v11 dst_sel:DWORD dst_unused:UNUSED_PAD src0_sel:WORD_1
	v_lshl_add_u64 v[4:5], v[4:5], 0, v[0:1]
	v_pk_mul_f32 v[16:17], v[58:59], v[16:17] op_sel_hi:[0,1]
	v_cvt_pk_f16_f32 v11, v16, v17
	v_cvt_f32_f16_e32 v16, v12
	v_cvt_f32_f16_sdwa v17, v12 dst_sel:DWORD dst_unused:UNUSED_PAD src0_sel:WORD_1
	v_pk_mul_f32 v[16:17], v[58:59], v[16:17] op_sel_hi:[0,1]
	v_cvt_pk_f16_f32 v12, v16, v17
	v_cvt_f32_f16_e32 v16, v13
	v_cvt_f32_f16_sdwa v17, v13 dst_sel:DWORD dst_unused:UNUSED_PAD src0_sel:WORD_1
	v_pk_mul_f32 v[16:17], v[58:59], v[16:17] op_sel_hi:[0,1]
	v_cvt_pk_f16_f32 v13, v16, v17
	global_store_dwordx4 v[4:5], v[10:13], off nt
.LBB0_637:
	s_or_b64 exec, exec, s[6:7]
	v_cmp_lt_i32_e32 vcc, v78, v33
	v_mad_u32_u24 v10, v77, s40, v14
	s_nop 0
	v_cndmask_b32_e32 v4, -1, v79, vcc
	v_cmp_lt_i32_e32 vcc, -1, v4
	s_and_saveexec_b64 s[6:7], vcc
	s_cbranch_execz .LBB0_639
	ds_read_b128 v[16:19], v10
	v_mov_b32_e32 v5, v149
	v_lshlrev_b64 v[4:5], 11, v[4:5]
	v_lshl_add_u64 v[4:5], s[18:19], 0, v[4:5]
	v_lshl_add_u64 v[4:5], s[4:5], 1, v[4:5]
	s_waitcnt lgkmcnt(0)
	v_cvt_f32_f16_e32 v12, v16
	v_cvt_f32_f16_sdwa v13, v16 dst_sel:DWORD dst_unused:UNUSED_PAD src0_sel:WORD_1
	v_mov_b32_e32 v3, v149
	v_lshl_add_u64 v[4:5], v[4:5], 0, v[2:3]
	v_mov_b32_e32 v1, v149
	v_pk_mul_f32 v[12:13], v[56:57], v[12:13] op_sel_hi:[0,1]
	v_cvt_pk_f16_f32 v16, v12, v13
	v_cvt_f32_f16_e32 v12, v17
	v_cvt_f32_f16_sdwa v13, v17 dst_sel:DWORD dst_unused:UNUSED_PAD src0_sel:WORD_1
	v_lshl_add_u64 v[4:5], v[4:5], 0, v[0:1]
	v_pk_mul_f32 v[12:13], v[56:57], v[12:13] op_sel_hi:[0,1]
	v_cvt_pk_f16_f32 v17, v12, v13
	v_cvt_f32_f16_e32 v12, v18
	v_cvt_f32_f16_sdwa v13, v18 dst_sel:DWORD dst_unused:UNUSED_PAD src0_sel:WORD_1
	v_pk_mul_f32 v[12:13], v[56:57], v[12:13] op_sel_hi:[0,1]
	v_cvt_pk_f16_f32 v18, v12, v13
	v_cvt_f32_f16_e32 v12, v19
	v_cvt_f32_f16_sdwa v13, v19 dst_sel:DWORD dst_unused:UNUSED_PAD src0_sel:WORD_1
	v_pk_mul_f32 v[12:13], v[56:57], v[12:13] op_sel_hi:[0,1]
	v_cvt_pk_f16_f32 v19, v12, v13
	global_store_dwordx4 v[4:5], v[16:19], off nt
.LBB0_639:
	s_or_b64 exec, exec, s[6:7]
	v_cmp_lt_i32_e32 vcc, v75, v33
	v_mad_u32_u24 v11, v74, s40, v14
	s_nop 0
	v_cndmask_b32_e32 v4, -1, v76, vcc
	v_cmp_lt_i32_e32 vcc, -1, v4
	s_and_saveexec_b64 s[6:7], vcc
	s_cbranch_execz .LBB0_641
	ds_read_b128 v[16:19], v11
	v_mov_b32_e32 v5, v149
	v_lshlrev_b64 v[4:5], 11, v[4:5]
	v_lshl_add_u64 v[4:5], s[18:19], 0, v[4:5]
	v_lshl_add_u64 v[4:5], s[4:5], 1, v[4:5]
	s_waitcnt lgkmcnt(0)
	v_cvt_f32_f16_e32 v12, v16
	v_cvt_f32_f16_sdwa v13, v16 dst_sel:DWORD dst_unused:UNUSED_PAD src0_sel:WORD_1
	v_mov_b32_e32 v3, v149
	v_lshl_add_u64 v[4:5], v[4:5], 0, v[2:3]
	v_mov_b32_e32 v1, v149
	v_pk_mul_f32 v[12:13], v[54:55], v[12:13] op_sel_hi:[0,1]
	v_cvt_pk_f16_f32 v16, v12, v13
	v_cvt_f32_f16_e32 v12, v17
	v_cvt_f32_f16_sdwa v13, v17 dst_sel:DWORD dst_unused:UNUSED_PAD src0_sel:WORD_1
	v_lshl_add_u64 v[4:5], v[4:5], 0, v[0:1]
	v_pk_mul_f32 v[12:13], v[54:55], v[12:13] op_sel_hi:[0,1]
	v_cvt_pk_f16_f32 v17, v12, v13
	v_cvt_f32_f16_e32 v12, v18
	v_cvt_f32_f16_sdwa v13, v18 dst_sel:DWORD dst_unused:UNUSED_PAD src0_sel:WORD_1
	v_pk_mul_f32 v[12:13], v[54:55], v[12:13] op_sel_hi:[0,1]
	v_cvt_pk_f16_f32 v18, v12, v13
	v_cvt_f32_f16_e32 v12, v19
	v_cvt_f32_f16_sdwa v13, v19 dst_sel:DWORD dst_unused:UNUSED_PAD src0_sel:WORD_1
	v_pk_mul_f32 v[12:13], v[54:55], v[12:13] op_sel_hi:[0,1]
	v_cvt_pk_f16_f32 v19, v12, v13
	global_store_dwordx4 v[4:5], v[16:19], off nt
; DI void moe_e2_phase(const Params& P, int l, char* smem, int* tb) {
;     ...
;         for (int i = 0; i < 8; i++) {
;           const int c = i * 64 + lane2, row = c >> 3, c16 = c & 7;
;           h8 v = *(const h8*)(stg + row * 144 + c16 * 16);
;           if (aa[h][i] >= 0) {
;             const float w = ww[h][i];
; #pragma unroll
;             for (int u = 0; u < 8; u++) v[u] = (half_t)(w * (float)v[u]);
;             *(h8*)(P.yA + (size_t)aa[h][i] * D + nt * 128 + wc2 * 64 + c16 * 8) = v;
;           }
;         }
.LBB0_641:
	s_or_b64 exec, exec, s[6:7]
	v_cmp_lt_i32_e32 vcc, v70, v33
	v_mad_u32_u24 v12, v69, s40, v14
	s_nop 0
	v_cndmask_b32_e32 v4, -1, v71, vcc
	v_cmp_lt_i32_e32 vcc, -1, v4
	s_and_saveexec_b64 s[6:7], vcc
	s_cbranch_execz .LBB0_643
	ds_read_b128 v[16:19], v12
	v_mov_b32_e32 v5, v149
	v_lshlrev_b64 v[4:5], 11, v[4:5]
	v_lshl_add_u64 v[4:5], s[18:19], 0, v[4:5]
	v_lshl_add_u64 v[4:5], s[4:5], 1, v[4:5]
	s_waitcnt lgkmcnt(0)
	v_cvt_f32_f16_e32 v20, v16
	v_cvt_f32_f16_sdwa v21, v16 dst_sel:DWORD dst_unused:UNUSED_PAD src0_sel:WORD_1
	v_mov_b32_e32 v3, v149
	v_lshl_add_u64 v[4:5], v[4:5], 0, v[2:3]
	v_mov_b32_e32 v1, v149
	v_pk_mul_f32 v[20:21], v[52:53], v[20:21] op_sel_hi:[0,1]
	v_cvt_pk_f16_f32 v16, v20, v21
	v_cvt_f32_f16_e32 v20, v17
	v_cvt_f32_f16_sdwa v21, v17 dst_sel:DWORD dst_unused:UNUSED_PAD src0_sel:WORD_1
	v_lshl_add_u64 v[4:5], v[4:5], 0, v[0:1]
	v_pk_mul_f32 v[20:21], v[52:53], v[20:21] op_sel_hi:[0,1]
	v_cvt_pk_f16_f32 v17, v20, v21
	v_cvt_f32_f16_e32 v20, v18
	v_cvt_f32_f16_sdwa v21, v18 dst_sel:DWORD dst_unused:UNUSED_PAD src0_sel:WORD_1
	v_pk_mul_f32 v[20:21], v[52:53], v[20:21] op_sel_hi:[0,1]
	v_cvt_pk_f16_f32 v18, v20, v21
	v_cvt_f32_f16_e32 v20, v19
	v_cvt_f32_f16_sdwa v21, v19 dst_sel:DWORD dst_unused:UNUSED_PAD src0_sel:WORD_1
	v_pk_mul_f32 v[20:21], v[52:53], v[20:21] op_sel_hi:[0,1]
	v_cvt_pk_f16_f32 v19, v20, v21
	global_store_dwordx4 v[4:5], v[16:19], off nt
.LBB0_643:
	s_or_b64 exec, exec, s[6:7]
	v_cmp_lt_i32_e32 vcc, v67, v33
	v_mad_u32_u24 v13, v66, s40, v14
	s_nop 0
	v_cndmask_b32_e32 v4, -1, v68, vcc
	v_cmp_lt_i32_e32 vcc, -1, v4
	s_and_saveexec_b64 s[6:7], vcc
	s_cbranch_execz .LBB0_645
	ds_read_b128 v[16:19], v13
	v_mov_b32_e32 v5, v149
	v_lshlrev_b64 v[4:5], 11, v[4:5]
	v_lshl_add_u64 v[4:5], s[18:19], 0, v[4:5]
	v_lshl_add_u64 v[4:5], s[4:5], 1, v[4:5]
	s_waitcnt lgkmcnt(0)
	v_cvt_f32_f16_e32 v20, v16
	v_cvt_f32_f16_sdwa v21, v16 dst_sel:DWORD dst_unused:UNUSED_PAD src0_sel:WORD_1
	v_mov_b32_e32 v3, v149
	v_lshl_add_u64 v[4:5], v[4:5], 0, v[2:3]
	v_mov_b32_e32 v1, v149
	v_pk_mul_f32 v[20:21], v[50:51], v[20:21] op_sel_hi:[0,1]
	v_cvt_pk_f16_f32 v16, v20, v21
	v_cvt_f32_f16_e32 v20, v17
	v_cvt_f32_f16_sdwa v21, v17 dst_sel:DWORD dst_unused:UNUSED_PAD src0_sel:WORD_1
	v_lshl_add_u64 v[4:5], v[4:5], 0, v[0:1]
	v_pk_mul_f32 v[20:21], v[50:51], v[20:21] op_sel_hi:[0,1]
	v_cvt_pk_f16_f32 v17, v20, v21
	v_cvt_f32_f16_e32 v20, v18
	v_cvt_f32_f16_sdwa v21, v18 dst_sel:DWORD dst_unused:UNUSED_PAD src0_sel:WORD_1
	v_pk_mul_f32 v[20:21], v[50:51], v[20:21] op_sel_hi:[0,1]
	v_cvt_pk_f16_f32 v18, v20, v21
	v_cvt_f32_f16_e32 v20, v19
	v_cvt_f32_f16_sdwa v21, v19 dst_sel:DWORD dst_unused:UNUSED_PAD src0_sel:WORD_1
	v_pk_mul_f32 v[20:21], v[50:51], v[20:21] op_sel_hi:[0,1]
	v_cvt_pk_f16_f32 v19, v20, v21
	global_store_dwordx4 v[4:5], v[16:19], off nt
.LBB0_645:
	s_or_b64 exec, exec, s[6:7]
	v_cmp_lt_i32_e32 vcc, v64, v33
	v_mad_u32_u24 v14, v63, s40, v14
	s_nop 0
	v_cndmask_b32_e32 v4, -1, v65, vcc
	v_cmp_lt_i32_e32 vcc, -1, v4
	s_and_saveexec_b64 s[6:7], vcc
	s_cbranch_execz .LBB0_647
	ds_read_b128 v[16:19], v14
	v_mov_b32_e32 v5, v149
	v_lshlrev_b64 v[4:5], 11, v[4:5]
	v_lshl_add_u64 v[4:5], s[18:19], 0, v[4:5]
	v_lshl_add_u64 v[4:5], s[4:5], 1, v[4:5]
	s_waitcnt lgkmcnt(0)
	v_cvt_f32_f16_e32 v20, v16
	v_cvt_f32_f16_sdwa v21, v16 dst_sel:DWORD dst_unused:UNUSED_PAD src0_sel:WORD_1
	v_mov_b32_e32 v3, v149
	v_lshl_add_u64 v[4:5], v[4:5], 0, v[2:3]
	v_mov_b32_e32 v1, v149
	v_pk_mul_f32 v[20:21], v[48:49], v[20:21] op_sel_hi:[0,1]
	v_cvt_pk_f16_f32 v16, v20, v21
	v_cvt_f32_f16_e32 v20, v17
	v_cvt_f32_f16_sdwa v21, v17 dst_sel:DWORD dst_unused:UNUSED_PAD src0_sel:WORD_1
	v_lshl_add_u64 v[4:5], v[4:5], 0, v[0:1]
	v_pk_mul_f32 v[20:21], v[48:49], v[20:21] op_sel_hi:[0,1]
	v_cvt_pk_f16_f32 v17, v20, v21
	v_cvt_f32_f16_e32 v20, v18
	v_cvt_f32_f16_sdwa v21, v18 dst_sel:DWORD dst_unused:UNUSED_PAD src0_sel:WORD_1
	v_pk_mul_f32 v[20:21], v[48:49], v[20:21] op_sel_hi:[0,1]
	v_cvt_pk_f16_f32 v18, v20, v21
	v_cvt_f32_f16_e32 v20, v19
	v_cvt_f32_f16_sdwa v21, v19 dst_sel:DWORD dst_unused:UNUSED_PAD src0_sel:WORD_1
	v_pk_mul_f32 v[20:21], v[48:49], v[20:21] op_sel_hi:[0,1]
	v_cvt_pk_f16_f32 v19, v20, v21
	global_store_dwordx4 v[4:5], v[16:19], off nt
; DI void moe_e2_phase(const Params& P, int l, char* smem, int* tb) {
;     ...
;         for (int ml = 0; ml < 4; ml++)
; #pragma unroll
;           for (int n = 0; n < 4; n++)
; #pragma unroll
;             for (int j = 0; j < 4; j++) stage_put(stg, ml, n, j, fr2, fq2, acc[h * 4 + ml][n][j]);
;         __builtin_amdgcn_wave_barrier();
; #pragma unroll
;         for (int i = 0; i < 8; i++) {
;           const int c = i * 64 + lane2, row = c >> 3, c16 = c & 7;
;           h8 v = *(const h8*)(stg + row * 144 + c16 * 16);
;           if (aa[h][i] >= 0) {
;             const float w = ww[h][i];
; #pragma unroll
;             for (int u = 0; u < 8; u++) v[u] = (half_t)(w * (float)v[u]);
;             *(h8*)(P.yA + (size_t)aa[h][i] * D + nt * 128 + wc2 * 64 + c16 * 8) = v;
;           }
;         }
.LBB0_647:
	s_or_b64 exec, exec, s[6:7]
	v_cvt_f16_f32_e32 v1, v154
	v_cvt_f16_f32_e32 v3, v155
	v_cvt_f16_f32_e32 v5, v153
	v_cvt_f16_f32_e32 v15, v152
	ds_write_b16 v6, v1
	ds_write_b16 v6, v3 offset:144
	ds_write_b16 v6, v5 offset:288
	ds_write_b16 v6, v15 offset:432
	v_cvt_f16_f32_e32 v1, v151
	v_cvt_f16_f32_e32 v3, v147
	v_cvt_f16_f32_e32 v5, v150
	v_cvt_f16_f32_e32 v15, v146
	ds_write_b16 v6, v1 offset:32
	ds_write_b16 v6, v3 offset:176
	ds_write_b16 v6, v5 offset:320
	ds_write_b16 v6, v15 offset:464
	v_cvt_f16_f32_e32 v1, v145
	v_cvt_f16_f32_e32 v3, v144
	v_cvt_f16_f32_e32 v5, v142
	v_cvt_f16_f32_e32 v15, v143
	ds_write_b16 v6, v1 offset:64
	ds_write_b16 v6, v3 offset:208
	ds_write_b16 v6, v5 offset:352
	ds_write_b16 v6, v15 offset:496
	v_cvt_f16_f32_e32 v1, v140
	v_cvt_f16_f32_e32 v3, v141
	v_cvt_f16_f32_e32 v5, v139
	v_cvt_f16_f32_e32 v15, v138
	ds_write_b16 v6, v1 offset:96
	ds_write_b16 v6, v3 offset:240
	ds_write_b16 v6, v5 offset:384
	ds_write_b16 v6, v15 offset:528
	v_cvt_f16_f32_e32 v1, v137
	v_cvt_f16_f32_e32 v3, v135
	v_cvt_f16_f32_e32 v5, v136
	v_cvt_f16_f32_e32 v15, v134
	ds_write_b16 v6, v1 offset:2304
	ds_write_b16 v6, v3 offset:2448
	ds_write_b16 v6, v5 offset:2592
	ds_write_b16 v6, v15 offset:2736
	v_cvt_f16_f32_e32 v1, v133
	v_cvt_f16_f32_e32 v3, v132
	v_cvt_f16_f32_e32 v5, v130
	v_cvt_f16_f32_e32 v15, v131
	ds_write_b16 v6, v1 offset:2336
	ds_write_b16 v6, v3 offset:2480
	ds_write_b16 v6, v5 offset:2624
	ds_write_b16 v6, v15 offset:2768
	v_cvt_f16_f32_e32 v1, v128
	v_cvt_f16_f32_e32 v3, v129
	v_cvt_f16_f32_e32 v5, v127
	v_cvt_f16_f32_e32 v15, v126
	ds_write_b16 v6, v1 offset:2368
	ds_write_b16 v6, v3 offset:2512
	ds_write_b16 v6, v5 offset:2656
	ds_write_b16 v6, v15 offset:2800
	v_cvt_f16_f32_e32 v1, v125
	v_cvt_f16_f32_e32 v3, v123
	v_cvt_f16_f32_e32 v5, v124
	v_cvt_f16_f32_e32 v15, v122
	ds_write_b16 v6, v1 offset:2400
	ds_write_b16 v6, v3 offset:2544
	ds_write_b16 v6, v5 offset:2688
	ds_write_b16 v6, v15 offset:2832
	v_cvt_f16_f32_e32 v1, v121
	v_cvt_f16_f32_e32 v3, v120
	v_cvt_f16_f32_e32 v5, v118
	v_cvt_f16_f32_e32 v15, v119
	ds_write_b16 v6, v1 offset:4608
	ds_write_b16 v6, v3 offset:4752
	ds_write_b16 v6, v5 offset:4896
	ds_write_b16 v6, v15 offset:5040
	v_cvt_f16_f32_e32 v1, v116
	v_cvt_f16_f32_e32 v3, v117
	v_cvt_f16_f32_e32 v5, v115
	v_cvt_f16_f32_e32 v15, v114
	ds_write_b16 v6, v1 offset:4640
	ds_write_b16 v6, v3 offset:4784
	ds_write_b16 v6, v5 offset:4928
	ds_write_b16 v6, v15 offset:5072
	v_cvt_f16_f32_e32 v1, v113
	v_cvt_f16_f32_e32 v3, v111
	v_cvt_f16_f32_e32 v5, v112
	v_cvt_f16_f32_e32 v15, v110
	ds_write_b16 v6, v1 offset:4672
	ds_write_b16 v6, v3 offset:4816
	ds_write_b16 v6, v5 offset:4960
	ds_write_b16 v6, v15 offset:5104
	v_cvt_f16_f32_e32 v1, v109
	v_cvt_f16_f32_e32 v3, v108
	v_cvt_f16_f32_e32 v5, v106
	v_cvt_f16_f32_e32 v15, v107
	ds_write_b16 v6, v1 offset:4704
	ds_write_b16 v6, v3 offset:4848
	ds_write_b16 v6, v5 offset:4992
	ds_write_b16 v6, v15 offset:5136
	v_cvt_f16_f32_e32 v1, v104
	v_cvt_f16_f32_e32 v3, v105
	v_cvt_f16_f32_e32 v5, v103
	v_cvt_f16_f32_e32 v15, v102
	ds_write_b16 v6, v1 offset:6912
	ds_write_b16 v6, v3 offset:7056
	ds_write_b16 v6, v5 offset:7200
	ds_write_b16 v6, v15 offset:7344
	v_cvt_f16_f32_e32 v1, v101
	v_cvt_f16_f32_e32 v3, v99
	v_cvt_f16_f32_e32 v5, v100
	v_cvt_f16_f32_e32 v15, v98
	ds_write_b16 v6, v1 offset:6944
	ds_write_b16 v6, v3 offset:7088
	ds_write_b16 v6, v5 offset:7232
	ds_write_b16 v6, v15 offset:7376
	v_cvt_f16_f32_e32 v1, v97
	v_cvt_f16_f32_e32 v3, v96
	v_cvt_f16_f32_e32 v5, v94
	v_cvt_f16_f32_e32 v15, v95
	ds_write_b16 v6, v1 offset:6976
	ds_write_b16 v6, v3 offset:7120
	ds_write_b16 v6, v5 offset:7264
	ds_write_b16 v6, v15 offset:7408
	v_cvt_f16_f32_e32 v1, v92
	v_cmp_lt_i32_e32 vcc, v72, v33
	v_cvt_f16_f32_e32 v3, v93
	v_cvt_f16_f32_e32 v5, v91
	v_cndmask_b32_e32 v4, -1, v73, vcc
	v_cvt_f16_f32_e32 v15, v90
	v_cmp_lt_i32_e32 vcc, -1, v4
	ds_write_b16 v6, v1 offset:7008
	ds_write_b16 v6, v3 offset:7152
	ds_write_b16 v6, v5 offset:7296
	ds_write_b16 v6, v15 offset:7440
	s_and_saveexec_b64 s[6:7], vcc
	s_cbranch_execz .LBB0_649
	ds_read_b128 v[16:19], v7
	v_mov_b32_e32 v5, v149
	v_lshlrev_b64 v[4:5], 11, v[4:5]
	v_lshl_add_u64 v[4:5], s[18:19], 0, v[4:5]
	v_lshl_add_u64 v[4:5], s[4:5], 1, v[4:5]
	s_waitcnt lgkmcnt(0)
	v_cvt_f32_f16_e32 v6, v16
	v_cvt_f32_f16_sdwa v7, v16 dst_sel:DWORD dst_unused:UNUSED_PAD src0_sel:WORD_1
	v_mov_b32_e32 v3, v149
	v_lshl_add_u64 v[4:5], v[4:5], 0, v[2:3]
	v_mov_b32_e32 v1, v149
	v_pk_mul_f32 v[6:7], v[46:47], v[6:7] op_sel_hi:[0,1]
	v_cvt_pk_f16_f32 v16, v6, v7
	v_cvt_f32_f16_e32 v6, v17
	v_cvt_f32_f16_sdwa v7, v17 dst_sel:DWORD dst_unused:UNUSED_PAD src0_sel:WORD_1
	v_lshl_add_u64 v[4:5], v[4:5], 0, v[0:1]
	v_pk_mul_f32 v[6:7], v[46:47], v[6:7] op_sel_hi:[0,1]
	v_cvt_pk_f16_f32 v17, v6, v7
	v_cvt_f32_f16_e32 v6, v18
	v_cvt_f32_f16_sdwa v7, v18 dst_sel:DWORD dst_unused:UNUSED_PAD src0_sel:WORD_1
	v_pk_mul_f32 v[6:7], v[46:47], v[6:7] op_sel_hi:[0,1]
	v_cvt_pk_f16_f32 v18, v6, v7
	v_cvt_f32_f16_e32 v6, v19
	v_cvt_f32_f16_sdwa v7, v19 dst_sel:DWORD dst_unused:UNUSED_PAD src0_sel:WORD_1
	v_pk_mul_f32 v[6:7], v[46:47], v[6:7] op_sel_hi:[0,1]
	v_cvt_pk_f16_f32 v19, v6, v7
	global_store_dwordx4 v[4:5], v[16:19], off nt
; DI void moe_e2_phase(const Params& P, int l, char* smem, int* tb) {
;     ...
;         for (int i = 0; i < 8; i++) {
;           const int c = i * 64 + lane2, row = c >> 3, c16 = c & 7;
;           h8 v = *(const h8*)(stg + row * 144 + c16 * 16);
;           if (aa[h][i] >= 0) {
;             const float w = ww[h][i];
; #pragma unroll
;             for (int u = 0; u < 8; u++) v[u] = (half_t)(w * (float)v[u]);
;             *(h8*)(P.yA + (size_t)aa[h][i] * D + nt * 128 + wc2 * 64 + c16 * 8) = v;
;           }
;         }
.LBB0_649:
	s_or_b64 exec, exec, s[6:7]
	v_cmp_lt_i32_e32 vcc, v59, v33
	s_nop 1
	v_cndmask_b32_e32 v4, -1, v61, vcc
	v_cmp_lt_i32_e32 vcc, -1, v4
	s_and_saveexec_b64 s[6:7], vcc
	s_cbranch_execz .LBB0_651
	ds_read_b128 v[16:19], v8
	v_mov_b32_e32 v5, v149
	v_lshlrev_b64 v[4:5], 11, v[4:5]
	v_lshl_add_u64 v[4:5], s[18:19], 0, v[4:5]
	v_lshl_add_u64 v[4:5], s[4:5], 1, v[4:5]
	s_waitcnt lgkmcnt(0)
	v_cvt_f32_f16_e32 v6, v16
	v_cvt_f32_f16_sdwa v7, v16 dst_sel:DWORD dst_unused:UNUSED_PAD src0_sel:WORD_1
	v_mov_b32_e32 v3, v149
	v_lshl_add_u64 v[4:5], v[4:5], 0, v[2:3]
	v_mov_b32_e32 v1, v149
	v_pk_mul_f32 v[6:7], v[44:45], v[6:7] op_sel_hi:[0,1]
	v_cvt_pk_f16_f32 v16, v6, v7
	v_cvt_f32_f16_e32 v6, v17
	v_cvt_f32_f16_sdwa v7, v17 dst_sel:DWORD dst_unused:UNUSED_PAD src0_sel:WORD_1
	v_lshl_add_u64 v[4:5], v[4:5], 0, v[0:1]
	v_pk_mul_f32 v[6:7], v[44:45], v[6:7] op_sel_hi:[0,1]
	v_cvt_pk_f16_f32 v17, v6, v7
	v_cvt_f32_f16_e32 v6, v18
	v_cvt_f32_f16_sdwa v7, v18 dst_sel:DWORD dst_unused:UNUSED_PAD src0_sel:WORD_1
	v_pk_mul_f32 v[6:7], v[44:45], v[6:7] op_sel_hi:[0,1]
	v_cvt_pk_f16_f32 v18, v6, v7
	v_cvt_f32_f16_e32 v6, v19
	v_cvt_f32_f16_sdwa v7, v19 dst_sel:DWORD dst_unused:UNUSED_PAD src0_sel:WORD_1
	v_pk_mul_f32 v[6:7], v[44:45], v[6:7] op_sel_hi:[0,1]
	v_cvt_pk_f16_f32 v19, v6, v7
	global_store_dwordx4 v[4:5], v[16:19], off nt
.LBB0_651:
	s_or_b64 exec, exec, s[6:7]
	v_cmp_lt_i32_e32 vcc, v55, v33
	s_nop 1
	v_cndmask_b32_e32 v4, -1, v57, vcc
	v_cmp_lt_i32_e32 vcc, -1, v4
	s_and_saveexec_b64 s[6:7], vcc
	s_cbranch_execz .LBB0_653
	ds_read_b128 v[6:9], v9
	v_mov_b32_e32 v5, v149
	v_lshlrev_b64 v[4:5], 11, v[4:5]
	v_lshl_add_u64 v[4:5], s[18:19], 0, v[4:5]
	v_lshl_add_u64 v[4:5], s[4:5], 1, v[4:5]
	s_waitcnt lgkmcnt(0)
	v_cvt_f32_f16_e32 v16, v6
	v_cvt_f32_f16_sdwa v17, v6 dst_sel:DWORD dst_unused:UNUSED_PAD src0_sel:WORD_1
	v_mov_b32_e32 v3, v149
	v_lshl_add_u64 v[4:5], v[4:5], 0, v[2:3]
	v_mov_b32_e32 v1, v149
	v_pk_mul_f32 v[16:17], v[42:43], v[16:17] op_sel_hi:[0,1]
	v_cvt_pk_f16_f32 v6, v16, v17
	v_cvt_f32_f16_e32 v16, v7
	v_cvt_f32_f16_sdwa v17, v7 dst_sel:DWORD dst_unused:UNUSED_PAD src0_sel:WORD_1
	v_lshl_add_u64 v[4:5], v[4:5], 0, v[0:1]
	v_pk_mul_f32 v[16:17], v[42:43], v[16:17] op_sel_hi:[0,1]
	v_cvt_pk_f16_f32 v7, v16, v17
	v_cvt_f32_f16_e32 v16, v8
	v_cvt_f32_f16_sdwa v17, v8 dst_sel:DWORD dst_unused:UNUSED_PAD src0_sel:WORD_1
	v_pk_mul_f32 v[16:17], v[42:43], v[16:17] op_sel_hi:[0,1]
	v_cvt_pk_f16_f32 v8, v16, v17
	v_cvt_f32_f16_e32 v16, v9
	v_cvt_f32_f16_sdwa v17, v9 dst_sel:DWORD dst_unused:UNUSED_PAD src0_sel:WORD_1
	v_pk_mul_f32 v[16:17], v[42:43], v[16:17] op_sel_hi:[0,1]
	v_cvt_pk_f16_f32 v9, v16, v17
	global_store_dwordx4 v[4:5], v[6:9], off nt
.LBB0_653:
	s_or_b64 exec, exec, s[6:7]
	v_cmp_lt_i32_e32 vcc, v51, v33
	s_nop 1
	v_cndmask_b32_e32 v4, -1, v53, vcc
	v_cmp_lt_i32_e32 vcc, -1, v4
	s_and_saveexec_b64 s[6:7], vcc
	s_cbranch_execz .LBB0_655
	ds_read_b128 v[6:9], v10
	v_mov_b32_e32 v5, v149
	v_lshlrev_b64 v[4:5], 11, v[4:5]
	v_lshl_add_u64 v[4:5], s[18:19], 0, v[4:5]
	v_lshl_add_u64 v[4:5], s[4:5], 1, v[4:5]
	s_waitcnt lgkmcnt(0)
	v_cvt_f32_f16_e32 v16, v6
	v_cvt_f32_f16_sdwa v17, v6 dst_sel:DWORD dst_unused:UNUSED_PAD src0_sel:WORD_1
	v_mov_b32_e32 v3, v149
	v_lshl_add_u64 v[4:5], v[4:5], 0, v[2:3]
	v_mov_b32_e32 v1, v149
	v_pk_mul_f32 v[16:17], v[40:41], v[16:17] op_sel_hi:[0,1]
	v_cvt_pk_f16_f32 v6, v16, v17
	v_cvt_f32_f16_e32 v16, v7
	v_cvt_f32_f16_sdwa v17, v7 dst_sel:DWORD dst_unused:UNUSED_PAD src0_sel:WORD_1
	v_lshl_add_u64 v[4:5], v[4:5], 0, v[0:1]
	v_pk_mul_f32 v[16:17], v[40:41], v[16:17] op_sel_hi:[0,1]
	v_cvt_pk_f16_f32 v7, v16, v17
	v_cvt_f32_f16_e32 v16, v8
	v_cvt_f32_f16_sdwa v17, v8 dst_sel:DWORD dst_unused:UNUSED_PAD src0_sel:WORD_1
	v_pk_mul_f32 v[16:17], v[40:41], v[16:17] op_sel_hi:[0,1]
	v_cvt_pk_f16_f32 v8, v16, v17
	v_cvt_f32_f16_e32 v16, v9
	v_cvt_f32_f16_sdwa v17, v9 dst_sel:DWORD dst_unused:UNUSED_PAD src0_sel:WORD_1
	v_pk_mul_f32 v[16:17], v[40:41], v[16:17] op_sel_hi:[0,1]
	v_cvt_pk_f16_f32 v9, v16, v17
	global_store_dwordx4 v[4:5], v[6:9], off nt
.LBB0_655:
	s_or_b64 exec, exec, s[6:7]
	v_cmp_lt_i32_e32 vcc, v47, v33
	s_nop 1
	v_cndmask_b32_e32 v4, -1, v49, vcc
	v_cmp_lt_i32_e32 vcc, -1, v4
	s_and_saveexec_b64 s[6:7], vcc
	s_cbranch_execz .LBB0_657
	ds_read_b128 v[6:9], v11
	v_mov_b32_e32 v5, v149
	v_lshlrev_b64 v[4:5], 11, v[4:5]
	v_lshl_add_u64 v[4:5], s[18:19], 0, v[4:5]
	v_lshl_add_u64 v[4:5], s[4:5], 1, v[4:5]
	s_waitcnt lgkmcnt(0)
	v_cvt_f32_f16_e32 v10, v6
	v_cvt_f32_f16_sdwa v11, v6 dst_sel:DWORD dst_unused:UNUSED_PAD src0_sel:WORD_1
	v_mov_b32_e32 v3, v149
	v_lshl_add_u64 v[4:5], v[4:5], 0, v[2:3]
	v_mov_b32_e32 v1, v149
	v_pk_mul_f32 v[10:11], v[38:39], v[10:11] op_sel_hi:[0,1]
	v_cvt_pk_f16_f32 v6, v10, v11
	v_cvt_f32_f16_e32 v10, v7
	v_cvt_f32_f16_sdwa v11, v7 dst_sel:DWORD dst_unused:UNUSED_PAD src0_sel:WORD_1
	v_lshl_add_u64 v[4:5], v[4:5], 0, v[0:1]
	v_pk_mul_f32 v[10:11], v[38:39], v[10:11] op_sel_hi:[0,1]
	v_cvt_pk_f16_f32 v7, v10, v11
	v_cvt_f32_f16_e32 v10, v8
	v_cvt_f32_f16_sdwa v11, v8 dst_sel:DWORD dst_unused:UNUSED_PAD src0_sel:WORD_1
	v_pk_mul_f32 v[10:11], v[38:39], v[10:11] op_sel_hi:[0,1]
	v_cvt_pk_f16_f32 v8, v10, v11
	v_cvt_f32_f16_e32 v10, v9
	v_cvt_f32_f16_sdwa v11, v9 dst_sel:DWORD dst_unused:UNUSED_PAD src0_sel:WORD_1
	v_pk_mul_f32 v[10:11], v[38:39], v[10:11] op_sel_hi:[0,1]
	v_cvt_pk_f16_f32 v9, v10, v11
	global_store_dwordx4 v[4:5], v[6:9], off nt
; DI void moe_e2_phase(const Params& P, int l, char* smem, int* tb) {
;     ...
;         for (int i = 0; i < 8; i++) {
;           const int c = i * 64 + lane2, row = c >> 3, c16 = c & 7;
;           h8 v = *(const h8*)(stg + row * 144 + c16 * 16);
;           if (aa[h][i] >= 0) {
;             const float w = ww[h][i];
; #pragma unroll
;             for (int u = 0; u < 8; u++) v[u] = (half_t)(w * (float)v[u]);
;             *(h8*)(P.yA + (size_t)aa[h][i] * D + nt * 128 + wc2 * 64 + c16 * 8) = v;
;           }
;         }
.LBB0_657:
	s_or_b64 exec, exec, s[6:7]
	v_cmp_lt_i32_e32 vcc, v43, v33
	s_nop 1
	v_cndmask_b32_e32 v4, -1, v45, vcc
	v_cmp_lt_i32_e32 vcc, -1, v4
	s_and_saveexec_b64 s[6:7], vcc
	s_cbranch_execz .LBB0_659
	ds_read_b128 v[6:9], v12
	v_mov_b32_e32 v5, v149
	v_lshlrev_b64 v[4:5], 11, v[4:5]
	v_lshl_add_u64 v[4:5], s[18:19], 0, v[4:5]
	v_lshl_add_u64 v[4:5], s[4:5], 1, v[4:5]
	s_waitcnt lgkmcnt(0)
	v_cvt_f32_f16_e32 v10, v6
	v_cvt_f32_f16_sdwa v11, v6 dst_sel:DWORD dst_unused:UNUSED_PAD src0_sel:WORD_1
	v_mov_b32_e32 v3, v149
	v_lshl_add_u64 v[4:5], v[4:5], 0, v[2:3]
	v_mov_b32_e32 v1, v149
	v_pk_mul_f32 v[10:11], v[36:37], v[10:11] op_sel_hi:[0,1]
	v_cvt_pk_f16_f32 v6, v10, v11
	v_cvt_f32_f16_e32 v10, v7
	v_cvt_f32_f16_sdwa v11, v7 dst_sel:DWORD dst_unused:UNUSED_PAD src0_sel:WORD_1
	v_lshl_add_u64 v[4:5], v[4:5], 0, v[0:1]
	v_pk_mul_f32 v[10:11], v[36:37], v[10:11] op_sel_hi:[0,1]
	v_cvt_pk_f16_f32 v7, v10, v11
	v_cvt_f32_f16_e32 v10, v8
	v_cvt_f32_f16_sdwa v11, v8 dst_sel:DWORD dst_unused:UNUSED_PAD src0_sel:WORD_1
	v_pk_mul_f32 v[10:11], v[36:37], v[10:11] op_sel_hi:[0,1]
	v_cvt_pk_f16_f32 v8, v10, v11
	v_cvt_f32_f16_e32 v10, v9
	v_cvt_f32_f16_sdwa v11, v9 dst_sel:DWORD dst_unused:UNUSED_PAD src0_sel:WORD_1
	v_pk_mul_f32 v[10:11], v[36:37], v[10:11] op_sel_hi:[0,1]
	v_cvt_pk_f16_f32 v9, v10, v11
	global_store_dwordx4 v[4:5], v[6:9], off nt
.LBB0_659:
	s_or_b64 exec, exec, s[6:7]
	v_cmp_lt_i32_e32 vcc, v39, v33
	s_nop 1
	v_cndmask_b32_e32 v4, -1, v41, vcc
	v_cmp_lt_i32_e32 vcc, -1, v4
	s_and_saveexec_b64 s[6:7], vcc
	s_cbranch_execz .LBB0_661
	ds_read_b128 v[6:9], v13
	v_mov_b32_e32 v5, v149
	v_lshlrev_b64 v[4:5], 11, v[4:5]
	v_lshl_add_u64 v[4:5], s[18:19], 0, v[4:5]
	v_lshl_add_u64 v[4:5], s[4:5], 1, v[4:5]
	s_waitcnt lgkmcnt(0)
	v_cvt_f32_f16_e32 v10, v6
	v_cvt_f32_f16_sdwa v11, v6 dst_sel:DWORD dst_unused:UNUSED_PAD src0_sel:WORD_1
	v_mov_b32_e32 v3, v149
	v_lshl_add_u64 v[4:5], v[4:5], 0, v[2:3]
	v_mov_b32_e32 v1, v149
	v_pk_mul_f32 v[10:11], v[34:35], v[10:11] op_sel_hi:[0,1]
	v_cvt_pk_f16_f32 v6, v10, v11
	v_cvt_f32_f16_e32 v10, v7
	v_cvt_f32_f16_sdwa v11, v7 dst_sel:DWORD dst_unused:UNUSED_PAD src0_sel:WORD_1
	v_lshl_add_u64 v[4:5], v[4:5], 0, v[0:1]
	v_pk_mul_f32 v[10:11], v[34:35], v[10:11] op_sel_hi:[0,1]
	v_cvt_pk_f16_f32 v7, v10, v11
	v_cvt_f32_f16_e32 v10, v8
	v_cvt_f32_f16_sdwa v11, v8 dst_sel:DWORD dst_unused:UNUSED_PAD src0_sel:WORD_1
	v_pk_mul_f32 v[10:11], v[34:35], v[10:11] op_sel_hi:[0,1]
	v_cvt_pk_f16_f32 v8, v10, v11
	v_cvt_f32_f16_e32 v10, v9
	v_cvt_f32_f16_sdwa v11, v9 dst_sel:DWORD dst_unused:UNUSED_PAD src0_sel:WORD_1
	v_pk_mul_f32 v[10:11], v[34:35], v[10:11] op_sel_hi:[0,1]
	v_cvt_pk_f16_f32 v9, v10, v11
	global_store_dwordx4 v[4:5], v[6:9], off nt
.LBB0_661:
	s_or_b64 exec, exec, s[6:7]
	v_cmp_lt_i32_e32 vcc, v35, v33
	s_nop 1
	v_cndmask_b32_e32 v4, -1, v37, vcc
	v_cmp_lt_i32_e32 vcc, -1, v4
	s_and_saveexec_b64 s[6:7], vcc
	s_cbranch_execz .LBB0_610
	ds_read_b128 v[6:9], v14
	v_mov_b32_e32 v5, v149
	v_lshlrev_b64 v[4:5], 11, v[4:5]
	v_lshl_add_u64 v[4:5], s[18:19], 0, v[4:5]
	v_lshl_add_u64 v[4:5], s[4:5], 1, v[4:5]
	s_waitcnt lgkmcnt(0)
	v_cvt_f32_f16_e32 v10, v6
	v_cvt_f32_f16_sdwa v11, v6 dst_sel:DWORD dst_unused:UNUSED_PAD src0_sel:WORD_1
	v_mov_b32_e32 v3, v149
	v_lshl_add_u64 v[2:3], v[4:5], 0, v[2:3]
	v_mov_b32_e32 v1, v149
	v_pk_mul_f32 v[10:11], v[32:33], v[10:11] op_sel_hi:[0,1]
	v_cvt_pk_f16_f32 v6, v10, v11
	v_cvt_f32_f16_e32 v10, v7
	v_cvt_f32_f16_sdwa v11, v7 dst_sel:DWORD dst_unused:UNUSED_PAD src0_sel:WORD_1
	v_lshl_add_u64 v[0:1], v[2:3], 0, v[0:1]
	v_pk_mul_f32 v[10:11], v[32:33], v[10:11] op_sel_hi:[0,1]
	v_cvt_pk_f16_f32 v7, v10, v11
	v_cvt_f32_f16_e32 v10, v8
	v_cvt_f32_f16_sdwa v11, v8 dst_sel:DWORD dst_unused:UNUSED_PAD src0_sel:WORD_1
	v_pk_mul_f32 v[10:11], v[32:33], v[10:11] op_sel_hi:[0,1]
	v_cvt_pk_f16_f32 v8, v10, v11
	v_cvt_f32_f16_e32 v10, v9
	v_cvt_f32_f16_sdwa v11, v9 dst_sel:DWORD dst_unused:UNUSED_PAD src0_sel:WORD_1
	v_pk_mul_f32 v[10:11], v[32:33], v[10:11] op_sel_hi:[0,1]
	v_cvt_pk_f16_f32 v9, v10, v11
	global_store_dwordx4 v[0:1], v[6:9], off nt
	s_branch .LBB0_610
